# in-proj, FF1, FF2 GEMM loops: one s_barrier per superphase (waves 4-7 place it before their MFMA block, waves 0-3 after), MFMA prio 2 for waves 4-7; FF1/FF2 keep the original LDS-DMA staging order, in
# speedup vs baseline: 1.0065x; 1.0006x over previous
; #define PG8_STAGE(bufoff, gbase, voff) do { _Pragma("unroll") for (int _i = 0; _i < 2; ++_i) \
;         __builtin_amdgcn_global_load_lds((const unsigned*)((const char*)(gbase) + (voff)[_i]), (PG8_LAS unsigned*)(lds + (bufoff) + ldsw + _i * 8192), 16, 0, 0); } while (0)
; #define PG8_LDA(dst, b, h) do { _Pragma("unroll") for (int m = 0; m < 4; ++m) _Pragma("unroll") for (int k = 0; k < 2; ++k) dst[m][k] = *(const PG8_LAS bf16x8*)(lds + PG8_SA(b, h) + aoff + m * 2048 + k * 1024); } while (0)
; #define PG8_LDB(dst, b, h) do { _Pragma("unroll") for (int n = 0; n < 2; ++n) _Pragma("unroll") for (int k = 0; k < 2; ++k) dst[n][k] = *(const PG8_LAS bf16x8*)(lds + PG8_SB(b, h) + boff + n * 2048 + k * 1024); } while (0)
; #define PG8_MMA(ai, bj, At, Bt) do { __builtin_amdgcn_s_setprio(1); _Pragma("unroll") for (int m = 0; m < 4; ++m) _Pragma("unroll") for (int n = 0; n < 2; ++n) _Pragma("unroll") for (int k = 0; k < 2; ++k) \
;         acc[ai][bj][m][n] = __builtin_amdgcn_mfma_f32_16x16x32_bf16(Bt[n][k], At[m][k], acc[ai][bj][m][n], 0, 0, 0); __builtin_amdgcn_s_setprio(0); } while (0)
; #define PG8_WAIT_V(n) asm volatile("s_waitcnt vmcnt(" #n ")" ::: "memory")
; #define PG8_WAIT_L(n) asm volatile("s_waitcnt lgkmcnt(" #n ")" ::: "memory")
; #define PG8_BAR __builtin_amdgcn_s_barrier()
; #define PG8_SCHED __builtin_amdgcn_sched_barrier(0)
; template <class Epi, class Sched, bool ALIGN_EPI = false, bool SP2 = false>
; __device__ __forceinline__ void gemm_phase(PG8_LAS unsigned char* lds, const Gemm g, const Sched& S, const Epi& E) {
;     ...
;             PG8_LDB(B0, 0, 0); PG8_LDB(B1, 0, 1); PG8_SCHED; PG8_LDA(At, 0, 0); PG8_STAGE(PG8_SA(1, 1), a1 + hstep, voffA);
;             PG8_WAIT_V(8); PG8_WAIT_L(0); PG8_BAR; PG8_MMA(0, 0, At, B0); PG8_MMA(0, 1, At, B1); PG8_BAR; PG8_SCHED;
;             PG8_LDA(At, 0, 1); PG8_STAGE(PG8_SB(0, 0), b2, voffB); PG8_STAGE(PG8_SB(0, 1), b2 + hstep, voffB); PG8_STAGE(PG8_SA(0, 0), a2, voffA);
;             PG8_WAIT_V(8); PG8_WAIT_L(0); PG8_BAR; PG8_MMA(1, 0, At, B0); PG8_MMA(1, 1, At, B1); PG8_BAR; PG8_SCHED;
.LBB0_1251:
	ds_read_b128 v[130:133], v177
	ds_read_b128 v[134:137], v177 offset:1024
	ds_read_b128 v[138:141], v177 offset:2048
	ds_read_b128 v[142:145], v177 offset:3072
	ds_read_b128 v[162:165], v178
	ds_read_b128 v[180:183], v178 offset:1024
	ds_read_b128 v[184:187], v178 offset:2048
	ds_read_b128 v[188:191], v178 offset:3072
	s_add_u32 s40, s36, 0xfff00080
	s_addc_u32 s41, s37, -1
	s_cmp_eq_u32 s58, 60
	s_cselect_b32 s43, s15, s41
	s_cselect_b32 s42, s17, s40
	s_cselect_b32 s41, s54, s57
	s_cselect_b32 s40, s55, s56
	ds_read_b128 v[196:199], v179
	ds_read_b128 v[200:203], v179 offset:1024
	ds_read_b128 v[204:207], v179 offset:2048
	ds_read_b128 v[208:211], v179 offset:3072
	ds_read_b128 v[212:215], v179 offset:4096
	ds_read_b128 v[220:223], v179 offset:5120
	ds_read_b128 v[224:227], v179 offset:6144
	ds_read_b128 v[228:231], v179 offset:7168
	s_add_i32 m0, s24, 0xc000
	s_nop 0
	global_load_lds_dwordx4 v146, s[36:37]
	s_add_i32 m0, s24, 0xe000
	s_nop 0
	global_load_lds_dwordx4 v150, s[36:37]
	s_waitcnt lgkmcnt(0)
	s_setprio 1
	v_mfma_f32_16x16x32_bf16 v[126:129], v[130:133], v[196:199], v[126:129]
	v_mfma_f32_16x16x32_bf16 v[122:125], v[138:141], v[196:199], v[122:125]
	v_mfma_f32_16x16x32_bf16 v[110:113], v[130:133], v[204:207], v[110:113]
	v_mfma_f32_16x16x32_bf16 v[106:109], v[138:141], v[204:207], v[106:109]
	v_mfma_f32_16x16x32_bf16 v[94:97], v[130:133], v[212:215], v[94:97]
	v_mfma_f32_16x16x32_bf16 v[90:93], v[138:141], v[212:215], v[90:93]
	v_mfma_f32_16x16x32_bf16 v[78:81], v[130:133], v[224:227], v[78:81]
	v_mfma_f32_16x16x32_bf16 v[74:77], v[138:141], v[224:227], v[74:77]
	v_mfma_f32_16x16x32_bf16 v[126:129], v[134:137], v[200:203], v[126:129]
	v_mfma_f32_16x16x32_bf16 v[122:125], v[142:145], v[200:203], v[122:125]
	v_mfma_f32_16x16x32_bf16 v[110:113], v[134:137], v[208:211], v[110:113]
	v_mfma_f32_16x16x32_bf16 v[106:109], v[142:145], v[208:211], v[106:109]
	v_mfma_f32_16x16x32_bf16 v[94:97], v[134:137], v[220:223], v[94:97]
	v_mfma_f32_16x16x32_bf16 v[90:93], v[142:145], v[220:223], v[90:93]
	v_mfma_f32_16x16x32_bf16 v[78:81], v[134:137], v[228:231], v[78:81]
	v_mfma_f32_16x16x32_bf16 v[74:77], v[142:145], v[228:231], v[74:77]
	v_mfma_f32_16x16x32_bf16 v[118:121], v[162:165], v[196:199], v[118:121]
	v_mfma_f32_16x16x32_bf16 v[114:117], v[184:187], v[196:199], v[114:117]
	v_mfma_f32_16x16x32_bf16 v[102:105], v[162:165], v[204:207], v[102:105]
	v_mfma_f32_16x16x32_bf16 v[98:101], v[184:187], v[204:207], v[98:101]
	v_mfma_f32_16x16x32_bf16 v[86:89], v[162:165], v[212:215], v[86:89]
	v_mfma_f32_16x16x32_bf16 v[82:85], v[184:187], v[212:215], v[82:85]
	v_mfma_f32_16x16x32_bf16 v[70:73], v[162:165], v[224:227], v[70:73]
	v_mfma_f32_16x16x32_bf16 v[66:69], v[184:187], v[224:227], v[66:69]
	v_mfma_f32_16x16x32_bf16 v[118:121], v[180:183], v[200:203], v[118:121]
	v_mfma_f32_16x16x32_bf16 v[114:117], v[188:191], v[200:203], v[114:117]
	v_mfma_f32_16x16x32_bf16 v[102:105], v[180:183], v[208:211], v[102:105]
	v_mfma_f32_16x16x32_bf16 v[98:101], v[188:191], v[208:211], v[98:101]
	v_mfma_f32_16x16x32_bf16 v[86:89], v[180:183], v[220:223], v[86:89]
	v_mfma_f32_16x16x32_bf16 v[82:85], v[188:191], v[220:223], v[82:85]
	v_mfma_f32_16x16x32_bf16 v[70:73], v[180:183], v[228:231], v[70:73]
	v_mfma_f32_16x16x32_bf16 v[66:69], v[188:191], v[228:231], v[66:69]
	s_setprio 0
	s_waitcnt vmcnt(8)
	s_barrier
	ds_read_b128 v[196:199], v179 offset:16384
	ds_read_b128 v[200:203], v179 offset:17408
	ds_read_b128 v[204:207], v179 offset:18432
	ds_read_b128 v[208:211], v179 offset:19456
	ds_read_b128 v[212:215], v179 offset:20480
	ds_read_b128 v[220:223], v179 offset:21504
	ds_read_b128 v[224:227], v179 offset:22528
	ds_read_b128 v[228:231], v179 offset:23552
	s_add_u32 vcc_lo, s40, 0x100000
	s_addc_u32 vcc_hi, s41, 0
	s_add_i32 m0, s24, 0x10000
	s_nop 0
	global_load_lds_dwordx4 v148, s[40:41]
	s_add_i32 m0, s24, 0x12000
	s_nop 0
	global_load_lds_dwordx4 v152, s[40:41]
	s_add_i32 m0, s24, 0x14000
	s_nop 0
	global_load_lds_dwordx4 v148, vcc
	s_add_i32 m0, s24, 0x16000
	s_nop 0
	global_load_lds_dwordx4 v152, vcc
	s_mov_b32 m0, s24
	s_nop 0
	global_load_lds_dwordx4 v146, s[42:43]
	s_add_i32 m0, s24, 0x2000
	s_nop 0
	global_load_lds_dwordx4 v150, s[42:43]
	s_waitcnt lgkmcnt(0)
	s_setprio 1
	v_mfma_f32_16x16x32_bf16 v[62:65], v[130:133], v[196:199], v[62:65]
	v_mfma_f32_16x16x32_bf16 v[58:61], v[138:141], v[196:199], v[58:61]
	v_mfma_f32_16x16x32_bf16 v[46:49], v[130:133], v[204:207], v[46:49]
	v_mfma_f32_16x16x32_bf16 v[42:45], v[138:141], v[204:207], v[42:45]
	v_mfma_f32_16x16x32_bf16 v[30:33], v[130:133], v[212:215], v[30:33]
	v_mfma_f32_16x16x32_bf16 v[26:29], v[138:141], v[212:215], v[26:29]
	v_mfma_f32_16x16x32_bf16 v[14:17], v[130:133], v[224:227], v[14:17]
	v_mfma_f32_16x16x32_bf16 v[10:13], v[138:141], v[224:227], v[10:13]
	v_mfma_f32_16x16x32_bf16 v[62:65], v[134:137], v[200:203], v[62:65]
	v_mfma_f32_16x16x32_bf16 v[58:61], v[142:145], v[200:203], v[58:61]
	v_mfma_f32_16x16x32_bf16 v[46:49], v[134:137], v[208:211], v[46:49]
	v_mfma_f32_16x16x32_bf16 v[42:45], v[142:145], v[208:211], v[42:45]
	v_mfma_f32_16x16x32_bf16 v[30:33], v[134:137], v[220:223], v[30:33]
	v_mfma_f32_16x16x32_bf16 v[26:29], v[142:145], v[220:223], v[26:29]
	v_mfma_f32_16x16x32_bf16 v[14:17], v[134:137], v[228:231], v[14:17]
	v_mfma_f32_16x16x32_bf16 v[10:13], v[142:145], v[228:231], v[10:13]
	v_mfma_f32_16x16x32_bf16 v[54:57], v[162:165], v[196:199], v[54:57]
	v_mfma_f32_16x16x32_bf16 v[50:53], v[184:187], v[196:199], v[50:53]
	v_mfma_f32_16x16x32_bf16 v[38:41], v[162:165], v[204:207], v[38:41]
	v_mfma_f32_16x16x32_bf16 v[34:37], v[184:187], v[204:207], v[34:37]
	v_mfma_f32_16x16x32_bf16 v[22:25], v[162:165], v[212:215], v[22:25]
	v_mfma_f32_16x16x32_bf16 v[18:21], v[184:187], v[212:215], v[18:21]
	v_mfma_f32_16x16x32_bf16 v[6:9], v[162:165], v[224:227], v[6:9]
	v_mfma_f32_16x16x32_bf16 v[2:5], v[184:187], v[224:227], v[2:5]
	v_mfma_f32_16x16x32_bf16 v[54:57], v[180:183], v[200:203], v[54:57]
	v_mfma_f32_16x16x32_bf16 v[50:53], v[188:191], v[200:203], v[50:53]
	v_mfma_f32_16x16x32_bf16 v[38:41], v[180:183], v[208:211], v[38:41]
	v_mfma_f32_16x16x32_bf16 v[34:37], v[188:191], v[208:211], v[34:37]
	v_mfma_f32_16x16x32_bf16 v[22:25], v[180:183], v[220:223], v[22:25]
	v_mfma_f32_16x16x32_bf16 v[18:21], v[188:191], v[220:223], v[18:21]
	v_mfma_f32_16x16x32_bf16 v[6:9], v[180:183], v[228:231], v[6:9]
	v_mfma_f32_16x16x32_bf16 v[2:5], v[188:191], v[228:231], v[2:5]
	s_setprio 0
	s_waitcnt vmcnt(8)
	s_barrier
; #define PG8_STAGE(bufoff, gbase, voff) do { _Pragma("unroll") for (int _i = 0; _i < 2; ++_i) \
;         __builtin_amdgcn_global_load_lds((const unsigned*)((const char*)(gbase) + (voff)[_i]), (PG8_LAS unsigned*)(lds + (bufoff) + ldsw + _i * 8192), 16, 0, 0); } while (0)
; #define PG8_LDA(dst, b, h) do { _Pragma("unroll") for (int m = 0; m < 4; ++m) _Pragma("unroll") for (int k = 0; k < 2; ++k) dst[m][k] = *(const PG8_LAS bf16x8*)(lds + PG8_SA(b, h) + aoff + m * 2048 + k * 1024); } while (0)
; #define PG8_LDB(dst, b, h) do { _Pragma("unroll") for (int n = 0; n < 2; ++n) _Pragma("unroll") for (int k = 0; k < 2; ++k) dst[n][k] = *(const PG8_LAS bf16x8*)(lds + PG8_SB(b, h) + boff + n * 2048 + k * 1024); } while (0)
; #define PG8_MMA(ai, bj, At, Bt) do { __builtin_amdgcn_s_setprio(1); _Pragma("unroll") for (int m = 0; m < 4; ++m) _Pragma("unroll") for (int n = 0; n < 2; ++n) _Pragma("unroll") for (int k = 0; k < 2; ++k) \
;         acc[ai][bj][m][n] = __builtin_amdgcn_mfma_f32_16x16x32_bf16(Bt[n][k], At[m][k], acc[ai][bj][m][n], 0, 0, 0); __builtin_amdgcn_s_setprio(0); } while (0)
; #define PG8_WAIT_V(n) asm volatile("s_waitcnt vmcnt(" #n ")" ::: "memory")
; #define PG8_WAIT_L(n) asm volatile("s_waitcnt lgkmcnt(" #n ")" ::: "memory")
; #define PG8_BAR __builtin_amdgcn_s_barrier()
; #define PG8_SCHED __builtin_amdgcn_sched_barrier(0)
; template <class Epi, class Sched, bool ALIGN_EPI = false, bool SP2 = false>
; __device__ __forceinline__ void gemm_phase(PG8_LAS unsigned char* lds, const Gemm g, const Sched& S, const Epi& E) {
;     ...
;             PG8_LDB(B0, 1, 0); PG8_LDB(B1, 1, 1); PG8_SCHED; PG8_LDA(At, 1, 0); PG8_STAGE(PG8_SA(0, 1), a2 + hstep, voffA);
;             PG8_WAIT_V(8); PG8_WAIT_L(0); PG8_BAR; PG8_MMA(0, 0, At, B0); PG8_MMA(0, 1, At, B1); PG8_BAR; PG8_SCHED;
;             PG8_LDA(At, 1, 1); PG8_STAGE(PG8_SB(1, 0), b3, voffB); PG8_STAGE(PG8_SB(1, 1), b3 + hstep, voffB); PG8_STAGE(PG8_SA(1, 0), a3, voffA);
;             PG8_WAIT_V(8); PG8_WAIT_L(0); PG8_BAR; PG8_MMA(1, 0, At, B0); PG8_MMA(1, 1, At, B1); PG8_BAR; PG8_SCHED;
	s_add_i32 s59, 0, 0x18000
	s_add_i32 s60, 0, 0x1c000
	v_add_u32_e32 v142, s59, v166
	v_add_u32_e32 v188, s60, v166
	ds_read_b128 v[130:133], v142
	ds_read_b128 v[134:137], v142 offset:1024
	ds_read_b128 v[138:141], v142 offset:2048
	ds_read_b128 v[142:145], v142 offset:3072
	ds_read_b128 v[162:165], v188
	ds_read_b128 v[180:183], v188 offset:1024
	ds_read_b128 v[184:187], v188 offset:2048
	ds_read_b128 v[188:191], v188 offset:3072
	ds_read_b128 v[196:199], v179 offset:32768
	ds_read_b128 v[200:203], v179 offset:33792
	ds_read_b128 v[204:207], v179 offset:34816
	ds_read_b128 v[208:211], v179 offset:35840
	ds_read_b128 v[212:215], v179 offset:36864
	ds_read_b128 v[220:223], v179 offset:37888
	ds_read_b128 v[224:227], v179 offset:38912
	ds_read_b128 v[228:231], v179 offset:39936
	s_add_u32 vcc_lo, s42, 0x100000
	s_addc_u32 vcc_hi, s43, 0
	s_add_i32 m0, s24, 0x4000
	s_nop 0
	global_load_lds_dwordx4 v146, vcc
	s_add_i32 m0, s24, 0x6000
	s_nop 0
	global_load_lds_dwordx4 v150, vcc
	s_waitcnt lgkmcnt(0)
	s_setprio 1
	v_mfma_f32_16x16x32_bf16 v[126:129], v[130:133], v[196:199], v[126:129]
	v_mfma_f32_16x16x32_bf16 v[122:125], v[138:141], v[196:199], v[122:125]
	v_mfma_f32_16x16x32_bf16 v[110:113], v[130:133], v[204:207], v[110:113]
	v_mfma_f32_16x16x32_bf16 v[106:109], v[138:141], v[204:207], v[106:109]
	v_mfma_f32_16x16x32_bf16 v[94:97], v[130:133], v[212:215], v[94:97]
	v_mfma_f32_16x16x32_bf16 v[90:93], v[138:141], v[212:215], v[90:93]
	v_mfma_f32_16x16x32_bf16 v[78:81], v[130:133], v[224:227], v[78:81]
	v_mfma_f32_16x16x32_bf16 v[74:77], v[138:141], v[224:227], v[74:77]
	v_mfma_f32_16x16x32_bf16 v[126:129], v[134:137], v[200:203], v[126:129]
	v_mfma_f32_16x16x32_bf16 v[122:125], v[142:145], v[200:203], v[122:125]
	v_mfma_f32_16x16x32_bf16 v[110:113], v[134:137], v[208:211], v[110:113]
	v_mfma_f32_16x16x32_bf16 v[106:109], v[142:145], v[208:211], v[106:109]
	v_mfma_f32_16x16x32_bf16 v[94:97], v[134:137], v[220:223], v[94:97]
	v_mfma_f32_16x16x32_bf16 v[90:93], v[142:145], v[220:223], v[90:93]
	v_mfma_f32_16x16x32_bf16 v[78:81], v[134:137], v[228:231], v[78:81]
	v_mfma_f32_16x16x32_bf16 v[74:77], v[142:145], v[228:231], v[74:77]
	v_mfma_f32_16x16x32_bf16 v[118:121], v[162:165], v[196:199], v[118:121]
	v_mfma_f32_16x16x32_bf16 v[114:117], v[184:187], v[196:199], v[114:117]
	v_mfma_f32_16x16x32_bf16 v[102:105], v[162:165], v[204:207], v[102:105]
	v_mfma_f32_16x16x32_bf16 v[98:101], v[184:187], v[204:207], v[98:101]
	v_mfma_f32_16x16x32_bf16 v[86:89], v[162:165], v[212:215], v[86:89]
	v_mfma_f32_16x16x32_bf16 v[82:85], v[184:187], v[212:215], v[82:85]
	v_mfma_f32_16x16x32_bf16 v[70:73], v[162:165], v[224:227], v[70:73]
	v_mfma_f32_16x16x32_bf16 v[66:69], v[184:187], v[224:227], v[66:69]
	v_mfma_f32_16x16x32_bf16 v[118:121], v[180:183], v[200:203], v[118:121]
	v_mfma_f32_16x16x32_bf16 v[114:117], v[188:191], v[200:203], v[114:117]
	v_mfma_f32_16x16x32_bf16 v[102:105], v[180:183], v[208:211], v[102:105]
	v_mfma_f32_16x16x32_bf16 v[98:101], v[188:191], v[208:211], v[98:101]
	v_mfma_f32_16x16x32_bf16 v[86:89], v[180:183], v[220:223], v[86:89]
	v_mfma_f32_16x16x32_bf16 v[82:85], v[188:191], v[220:223], v[82:85]
	v_mfma_f32_16x16x32_bf16 v[70:73], v[180:183], v[228:231], v[70:73]
	v_mfma_f32_16x16x32_bf16 v[66:69], v[188:191], v[228:231], v[66:69]
	s_setprio 0
	s_waitcnt vmcnt(8)
	s_barrier
	ds_read_b128 v[196:199], v179 offset:49152
	ds_read_b128 v[200:203], v179 offset:50176
	ds_read_b128 v[204:207], v179 offset:51200
	ds_read_b128 v[208:211], v179 offset:52224
	ds_read_b128 v[212:215], v179 offset:53248
	ds_read_b128 v[220:223], v179 offset:54272
	ds_read_b128 v[224:227], v179 offset:55296
	ds_read_b128 v[228:231], v179 offset:56320
	s_add_u32 s60, s40, 0x80
	s_addc_u32 s61, s41, 0
	s_add_u32 vcc_lo, s60, 0x100000
	s_addc_u32 vcc_hi, s61, 0
	s_add_i32 m0, s24, 0x18000
	s_nop 0
	global_load_lds_dwordx4 v148, s[60:61]
	s_add_i32 m0, s24, 0x1a000
	s_nop 0
	global_load_lds_dwordx4 v152, s[60:61]
	s_add_i32 m0, s24, 0x1c000
	s_nop 0
	global_load_lds_dwordx4 v148, vcc
	s_add_i32 m0, s24, 0x1e000
	s_nop 0
	global_load_lds_dwordx4 v152, vcc
	s_add_u32 s60, s42, 0x80
	s_addc_u32 s61, s43, 0
	s_add_i32 m0, s24, 0x8000
	s_nop 0
	global_load_lds_dwordx4 v146, s[60:61]
	s_add_i32 m0, s24, 0xa000
	s_nop 0
	global_load_lds_dwordx4 v150, s[60:61]
	s_waitcnt lgkmcnt(0)
	s_setprio 1
	v_mfma_f32_16x16x32_bf16 v[62:65], v[130:133], v[196:199], v[62:65]
	v_mfma_f32_16x16x32_bf16 v[58:61], v[138:141], v[196:199], v[58:61]
	v_mfma_f32_16x16x32_bf16 v[46:49], v[130:133], v[204:207], v[46:49]
	v_mfma_f32_16x16x32_bf16 v[42:45], v[138:141], v[204:207], v[42:45]
	v_mfma_f32_16x16x32_bf16 v[30:33], v[130:133], v[212:215], v[30:33]
	v_mfma_f32_16x16x32_bf16 v[26:29], v[138:141], v[212:215], v[26:29]
	v_mfma_f32_16x16x32_bf16 v[14:17], v[130:133], v[224:227], v[14:17]
	v_mfma_f32_16x16x32_bf16 v[10:13], v[138:141], v[224:227], v[10:13]
	v_mfma_f32_16x16x32_bf16 v[62:65], v[134:137], v[200:203], v[62:65]
	v_mfma_f32_16x16x32_bf16 v[58:61], v[142:145], v[200:203], v[58:61]
	v_mfma_f32_16x16x32_bf16 v[46:49], v[134:137], v[208:211], v[46:49]
	v_mfma_f32_16x16x32_bf16 v[42:45], v[142:145], v[208:211], v[42:45]
	v_mfma_f32_16x16x32_bf16 v[30:33], v[134:137], v[220:223], v[30:33]
	v_mfma_f32_16x16x32_bf16 v[26:29], v[142:145], v[220:223], v[26:29]
	v_mfma_f32_16x16x32_bf16 v[14:17], v[134:137], v[228:231], v[14:17]
	v_mfma_f32_16x16x32_bf16 v[10:13], v[142:145], v[228:231], v[10:13]
	v_mfma_f32_16x16x32_bf16 v[54:57], v[162:165], v[196:199], v[54:57]
	v_mfma_f32_16x16x32_bf16 v[50:53], v[184:187], v[196:199], v[50:53]
	v_mfma_f32_16x16x32_bf16 v[38:41], v[162:165], v[204:207], v[38:41]
	v_mfma_f32_16x16x32_bf16 v[34:37], v[184:187], v[204:207], v[34:37]
	v_mfma_f32_16x16x32_bf16 v[22:25], v[162:165], v[212:215], v[22:25]
	v_mfma_f32_16x16x32_bf16 v[18:21], v[184:187], v[212:215], v[18:21]
	v_mfma_f32_16x16x32_bf16 v[6:9], v[162:165], v[224:227], v[6:9]
	v_mfma_f32_16x16x32_bf16 v[2:5], v[184:187], v[224:227], v[2:5]
	v_mfma_f32_16x16x32_bf16 v[54:57], v[180:183], v[200:203], v[54:57]
	v_mfma_f32_16x16x32_bf16 v[50:53], v[188:191], v[200:203], v[50:53]
	v_mfma_f32_16x16x32_bf16 v[38:41], v[180:183], v[208:211], v[38:41]
	v_mfma_f32_16x16x32_bf16 v[34:37], v[188:191], v[208:211], v[34:37]
	v_mfma_f32_16x16x32_bf16 v[22:25], v[180:183], v[220:223], v[22:25]
	v_mfma_f32_16x16x32_bf16 v[18:21], v[188:191], v[220:223], v[18:21]
	v_mfma_f32_16x16x32_bf16 v[6:9], v[180:183], v[228:231], v[6:9]
	v_mfma_f32_16x16x32_bf16 v[2:5], v[188:191], v[228:231], v[2:5]
	s_setprio 0
	s_waitcnt vmcnt(8)
	s_barrier
	s_add_i32 s58, s58, 2
	s_add_u32 s36, s36, 0x100
	s_addc_u32 s37, s37, 0
	s_add_u32 s56, s56, 0x100
	s_addc_u32 s57, s57, 0
	s_cmp_gt_u32 s58, 61
	s_cbranch_scc0 .LBB0_1251
	s_branch .Lf1_exit
; #define PG8_STAGE(bufoff, gbase, voff) do { _Pragma("unroll") for (int _i = 0; _i < 2; ++_i) \
;         __builtin_amdgcn_global_load_lds((const unsigned*)((const char*)(gbase) + (voff)[_i]), (PG8_LAS unsigned*)(lds + (bufoff) + ldsw + _i * 8192), 16, 0, 0); } while (0)
; #define PG8_LDA(dst, b, h) do { _Pragma("unroll") for (int m = 0; m < 4; ++m) _Pragma("unroll") for (int k = 0; k < 2; ++k) dst[m][k] = *(const PG8_LAS bf16x8*)(lds + PG8_SA(b, h) + aoff + m * 2048 + k * 1024); } while (0)
; #define PG8_LDB(dst, b, h) do { _Pragma("unroll") for (int n = 0; n < 2; ++n) _Pragma("unroll") for (int k = 0; k < 2; ++k) dst[n][k] = *(const PG8_LAS bf16x8*)(lds + PG8_SB(b, h) + boff + n * 2048 + k * 1024); } while (0)
; #define PG8_MMA(ai, bj, At, Bt) do { __builtin_amdgcn_s_setprio(1); _Pragma("unroll") for (int m = 0; m < 4; ++m) _Pragma("unroll") for (int n = 0; n < 2; ++n) _Pragma("unroll") for (int k = 0; k < 2; ++k) \
;         acc[ai][bj][m][n] = __builtin_amdgcn_mfma_f32_16x16x32_bf16(Bt[n][k], At[m][k], acc[ai][bj][m][n], 0, 0, 0); __builtin_amdgcn_s_setprio(0); } while (0)
; #define PG8_WAIT_V(n) asm volatile("s_waitcnt vmcnt(" #n ")" ::: "memory")
; #define PG8_WAIT_L(n) asm volatile("s_waitcnt lgkmcnt(" #n ")" ::: "memory")
; #define PG8_BAR __builtin_amdgcn_s_barrier()
; #define PG8_SCHED __builtin_amdgcn_sched_barrier(0)
; template <class Epi, class Sched, bool ALIGN_EPI = false, bool SP2 = false>
; __device__ __forceinline__ void gemm_phase(PG8_LAS unsigned char* lds, const Gemm g, const Sched& S, const Epi& E) {
;     ...
;             PG8_LDB(B0, 0, 0); PG8_LDB(B1, 0, 1); PG8_SCHED; PG8_LDA(At, 0, 0); PG8_STAGE(PG8_SA(1, 1), a1 + hstep, voffA);
;             PG8_WAIT_V(8); PG8_WAIT_L(0); PG8_BAR; PG8_MMA(0, 0, At, B0); PG8_MMA(0, 1, At, B1); PG8_BAR; PG8_SCHED;
;             PG8_LDA(At, 0, 1); PG8_STAGE(PG8_SB(0, 0), b2, voffB); PG8_STAGE(PG8_SB(0, 1), b2 + hstep, voffB); PG8_STAGE(PG8_SA(0, 0), a2, voffA);
;             PG8_WAIT_V(8); PG8_WAIT_L(0); PG8_BAR; PG8_MMA(1, 0, At, B0); PG8_MMA(1, 1, At, B1); PG8_BAR; PG8_SCHED;
.Lf1_h1:
	ds_read_b128 v[130:133], v177
	ds_read_b128 v[134:137], v177 offset:1024
	ds_read_b128 v[138:141], v177 offset:2048
	ds_read_b128 v[142:145], v177 offset:3072
	ds_read_b128 v[162:165], v178
	ds_read_b128 v[180:183], v178 offset:1024
	ds_read_b128 v[184:187], v178 offset:2048
	ds_read_b128 v[188:191], v178 offset:3072
	s_add_u32 s40, s36, 0xfff00080
	s_addc_u32 s41, s37, -1
	s_cmp_eq_u32 s58, 60
	s_cselect_b32 s43, s15, s41
	s_cselect_b32 s42, s17, s40
	s_cselect_b32 s41, s54, s57
	s_cselect_b32 s40, s55, s56
	ds_read_b128 v[196:199], v179
	ds_read_b128 v[200:203], v179 offset:1024
	ds_read_b128 v[204:207], v179 offset:2048
	ds_read_b128 v[208:211], v179 offset:3072
	ds_read_b128 v[212:215], v179 offset:4096
	ds_read_b128 v[220:223], v179 offset:5120
	ds_read_b128 v[224:227], v179 offset:6144
	ds_read_b128 v[228:231], v179 offset:7168
	s_add_i32 m0, s24, 0xc000
	s_nop 0
	global_load_lds_dwordx4 v146, s[36:37]
	s_add_i32 m0, s24, 0xe000
	s_nop 0
	global_load_lds_dwordx4 v150, s[36:37]
	s_sleep 2
	s_waitcnt lgkmcnt(0)
	s_waitcnt vmcnt(8)
	s_barrier
	s_setprio 2
	v_mfma_f32_16x16x32_bf16 v[126:129], v[130:133], v[196:199], v[126:129]
	v_mfma_f32_16x16x32_bf16 v[122:125], v[138:141], v[196:199], v[122:125]
	v_mfma_f32_16x16x32_bf16 v[110:113], v[130:133], v[204:207], v[110:113]
	v_mfma_f32_16x16x32_bf16 v[106:109], v[138:141], v[204:207], v[106:109]
	v_mfma_f32_16x16x32_bf16 v[94:97], v[130:133], v[212:215], v[94:97]
	v_mfma_f32_16x16x32_bf16 v[90:93], v[138:141], v[212:215], v[90:93]
	v_mfma_f32_16x16x32_bf16 v[78:81], v[130:133], v[224:227], v[78:81]
	v_mfma_f32_16x16x32_bf16 v[74:77], v[138:141], v[224:227], v[74:77]
	v_mfma_f32_16x16x32_bf16 v[126:129], v[134:137], v[200:203], v[126:129]
	v_mfma_f32_16x16x32_bf16 v[122:125], v[142:145], v[200:203], v[122:125]
	v_mfma_f32_16x16x32_bf16 v[110:113], v[134:137], v[208:211], v[110:113]
	v_mfma_f32_16x16x32_bf16 v[106:109], v[142:145], v[208:211], v[106:109]
	v_mfma_f32_16x16x32_bf16 v[94:97], v[134:137], v[220:223], v[94:97]
	v_mfma_f32_16x16x32_bf16 v[90:93], v[142:145], v[220:223], v[90:93]
	v_mfma_f32_16x16x32_bf16 v[78:81], v[134:137], v[228:231], v[78:81]
	v_mfma_f32_16x16x32_bf16 v[74:77], v[142:145], v[228:231], v[74:77]
	v_mfma_f32_16x16x32_bf16 v[118:121], v[162:165], v[196:199], v[118:121]
	v_mfma_f32_16x16x32_bf16 v[114:117], v[184:187], v[196:199], v[114:117]
	v_mfma_f32_16x16x32_bf16 v[102:105], v[162:165], v[204:207], v[102:105]
	v_mfma_f32_16x16x32_bf16 v[98:101], v[184:187], v[204:207], v[98:101]
	v_mfma_f32_16x16x32_bf16 v[86:89], v[162:165], v[212:215], v[86:89]
	v_mfma_f32_16x16x32_bf16 v[82:85], v[184:187], v[212:215], v[82:85]
	v_mfma_f32_16x16x32_bf16 v[70:73], v[162:165], v[224:227], v[70:73]
	v_mfma_f32_16x16x32_bf16 v[66:69], v[184:187], v[224:227], v[66:69]
	v_mfma_f32_16x16x32_bf16 v[118:121], v[180:183], v[200:203], v[118:121]
	v_mfma_f32_16x16x32_bf16 v[114:117], v[188:191], v[200:203], v[114:117]
	v_mfma_f32_16x16x32_bf16 v[102:105], v[180:183], v[208:211], v[102:105]
	v_mfma_f32_16x16x32_bf16 v[98:101], v[188:191], v[208:211], v[98:101]
	v_mfma_f32_16x16x32_bf16 v[86:89], v[180:183], v[220:223], v[86:89]
	v_mfma_f32_16x16x32_bf16 v[82:85], v[188:191], v[220:223], v[82:85]
	v_mfma_f32_16x16x32_bf16 v[70:73], v[180:183], v[228:231], v[70:73]
	v_mfma_f32_16x16x32_bf16 v[66:69], v[188:191], v[228:231], v[66:69]
	s_setprio 0
	ds_read_b128 v[196:199], v179 offset:16384
	ds_read_b128 v[200:203], v179 offset:17408
	ds_read_b128 v[204:207], v179 offset:18432
	ds_read_b128 v[208:211], v179 offset:19456
	ds_read_b128 v[212:215], v179 offset:20480
	ds_read_b128 v[220:223], v179 offset:21504
	ds_read_b128 v[224:227], v179 offset:22528
	ds_read_b128 v[228:231], v179 offset:23552
	s_add_u32 vcc_lo, s40, 0x100000
	s_addc_u32 vcc_hi, s41, 0
	s_add_i32 m0, s24, 0x10000
	s_nop 0
	global_load_lds_dwordx4 v148, s[40:41]
	s_add_i32 m0, s24, 0x12000
	s_nop 0
	global_load_lds_dwordx4 v152, s[40:41]
	s_add_i32 m0, s24, 0x14000
	s_nop 0
	global_load_lds_dwordx4 v148, vcc
	s_add_i32 m0, s24, 0x16000
	s_nop 0
	global_load_lds_dwordx4 v152, vcc
	s_mov_b32 m0, s24
	s_nop 0
	global_load_lds_dwordx4 v146, s[42:43]
	s_add_i32 m0, s24, 0x2000
	s_nop 0
	global_load_lds_dwordx4 v150, s[42:43]
	s_sleep 2
	s_waitcnt lgkmcnt(0)
	s_waitcnt vmcnt(8)
	s_barrier
; #define PG8_STAGE(bufoff, gbase, voff) do { _Pragma("unroll") for (int _i = 0; _i < 2; ++_i) \
;         __builtin_amdgcn_global_load_lds((const unsigned*)((const char*)(gbase) + (voff)[_i]), (PG8_LAS unsigned*)(lds + (bufoff) + ldsw + _i * 8192), 16, 0, 0); } while (0)
; #define PG8_LDA(dst, b, h) do { _Pragma("unroll") for (int m = 0; m < 4; ++m) _Pragma("unroll") for (int k = 0; k < 2; ++k) dst[m][k] = *(const PG8_LAS bf16x8*)(lds + PG8_SA(b, h) + aoff + m * 2048 + k * 1024); } while (0)
; #define PG8_LDB(dst, b, h) do { _Pragma("unroll") for (int n = 0; n < 2; ++n) _Pragma("unroll") for (int k = 0; k < 2; ++k) dst[n][k] = *(const PG8_LAS bf16x8*)(lds + PG8_SB(b, h) + boff + n * 2048 + k * 1024); } while (0)
; #define PG8_MMA(ai, bj, At, Bt) do { __builtin_amdgcn_s_setprio(1); _Pragma("unroll") for (int m = 0; m < 4; ++m) _Pragma("unroll") for (int n = 0; n < 2; ++n) _Pragma("unroll") for (int k = 0; k < 2; ++k) \
;         acc[ai][bj][m][n] = __builtin_amdgcn_mfma_f32_16x16x32_bf16(Bt[n][k], At[m][k], acc[ai][bj][m][n], 0, 0, 0); __builtin_amdgcn_s_setprio(0); } while (0)
; #define PG8_WAIT_V(n) asm volatile("s_waitcnt vmcnt(" #n ")" ::: "memory")
; #define PG8_WAIT_L(n) asm volatile("s_waitcnt lgkmcnt(" #n ")" ::: "memory")
; #define PG8_BAR __builtin_amdgcn_s_barrier()
; #define PG8_SCHED __builtin_amdgcn_sched_barrier(0)
; template <class Epi, class Sched, bool ALIGN_EPI = false, bool SP2 = false>
; __device__ __forceinline__ void gemm_phase(PG8_LAS unsigned char* lds, const Gemm g, const Sched& S, const Epi& E) {
;     ...
;             PG8_WAIT_V(8); PG8_WAIT_L(0); PG8_BAR; PG8_MMA(0, 0, At, B0); PG8_MMA(0, 1, At, B1); PG8_BAR; PG8_SCHED;
;             PG8_LDA(At, 0, 1); PG8_STAGE(PG8_SB(0, 0), b2, voffB); PG8_STAGE(PG8_SB(0, 1), b2 + hstep, voffB); PG8_STAGE(PG8_SA(0, 0), a2, voffA);
;             PG8_WAIT_V(8); PG8_WAIT_L(0); PG8_BAR; PG8_MMA(1, 0, At, B0); PG8_MMA(1, 1, At, B1); PG8_BAR; PG8_SCHED;
;             PG8_LDB(B0, 1, 0); PG8_LDB(B1, 1, 1); PG8_SCHED; PG8_LDA(At, 1, 0); PG8_STAGE(PG8_SA(0, 1), a2 + hstep, voffA);
;             PG8_WAIT_V(8); PG8_WAIT_L(0); PG8_BAR; PG8_MMA(0, 0, At, B0); PG8_MMA(0, 1, At, B1); PG8_BAR; PG8_SCHED;
	s_setprio 2
	v_mfma_f32_16x16x32_bf16 v[62:65], v[130:133], v[196:199], v[62:65]
	v_mfma_f32_16x16x32_bf16 v[58:61], v[138:141], v[196:199], v[58:61]
	v_mfma_f32_16x16x32_bf16 v[46:49], v[130:133], v[204:207], v[46:49]
	v_mfma_f32_16x16x32_bf16 v[42:45], v[138:141], v[204:207], v[42:45]
	v_mfma_f32_16x16x32_bf16 v[30:33], v[130:133], v[212:215], v[30:33]
	v_mfma_f32_16x16x32_bf16 v[26:29], v[138:141], v[212:215], v[26:29]
	v_mfma_f32_16x16x32_bf16 v[14:17], v[130:133], v[224:227], v[14:17]
	v_mfma_f32_16x16x32_bf16 v[10:13], v[138:141], v[224:227], v[10:13]
	v_mfma_f32_16x16x32_bf16 v[62:65], v[134:137], v[200:203], v[62:65]
	v_mfma_f32_16x16x32_bf16 v[58:61], v[142:145], v[200:203], v[58:61]
	v_mfma_f32_16x16x32_bf16 v[46:49], v[134:137], v[208:211], v[46:49]
	v_mfma_f32_16x16x32_bf16 v[42:45], v[142:145], v[208:211], v[42:45]
	v_mfma_f32_16x16x32_bf16 v[30:33], v[134:137], v[220:223], v[30:33]
	v_mfma_f32_16x16x32_bf16 v[26:29], v[142:145], v[220:223], v[26:29]
	v_mfma_f32_16x16x32_bf16 v[14:17], v[134:137], v[228:231], v[14:17]
	v_mfma_f32_16x16x32_bf16 v[10:13], v[142:145], v[228:231], v[10:13]
	v_mfma_f32_16x16x32_bf16 v[54:57], v[162:165], v[196:199], v[54:57]
	v_mfma_f32_16x16x32_bf16 v[50:53], v[184:187], v[196:199], v[50:53]
	v_mfma_f32_16x16x32_bf16 v[38:41], v[162:165], v[204:207], v[38:41]
	v_mfma_f32_16x16x32_bf16 v[34:37], v[184:187], v[204:207], v[34:37]
	v_mfma_f32_16x16x32_bf16 v[22:25], v[162:165], v[212:215], v[22:25]
	v_mfma_f32_16x16x32_bf16 v[18:21], v[184:187], v[212:215], v[18:21]
	v_mfma_f32_16x16x32_bf16 v[6:9], v[162:165], v[224:227], v[6:9]
	v_mfma_f32_16x16x32_bf16 v[2:5], v[184:187], v[224:227], v[2:5]
	v_mfma_f32_16x16x32_bf16 v[54:57], v[180:183], v[200:203], v[54:57]
	v_mfma_f32_16x16x32_bf16 v[50:53], v[188:191], v[200:203], v[50:53]
	v_mfma_f32_16x16x32_bf16 v[38:41], v[180:183], v[208:211], v[38:41]
	v_mfma_f32_16x16x32_bf16 v[34:37], v[188:191], v[208:211], v[34:37]
	v_mfma_f32_16x16x32_bf16 v[22:25], v[180:183], v[220:223], v[22:25]
	v_mfma_f32_16x16x32_bf16 v[18:21], v[188:191], v[220:223], v[18:21]
	v_mfma_f32_16x16x32_bf16 v[6:9], v[180:183], v[228:231], v[6:9]
	v_mfma_f32_16x16x32_bf16 v[2:5], v[188:191], v[228:231], v[2:5]
	s_setprio 0
	s_add_i32 s59, 0, 0x18000
	s_add_i32 s60, 0, 0x1c000
	v_add_u32_e32 v142, s59, v166
	v_add_u32_e32 v188, s60, v166
	ds_read_b128 v[130:133], v142
	ds_read_b128 v[134:137], v142 offset:1024
	ds_read_b128 v[138:141], v142 offset:2048
	ds_read_b128 v[142:145], v142 offset:3072
	ds_read_b128 v[162:165], v188
	ds_read_b128 v[180:183], v188 offset:1024
	ds_read_b128 v[184:187], v188 offset:2048
	ds_read_b128 v[188:191], v188 offset:3072
	ds_read_b128 v[196:199], v179 offset:32768
	ds_read_b128 v[200:203], v179 offset:33792
	ds_read_b128 v[204:207], v179 offset:34816
	ds_read_b128 v[208:211], v179 offset:35840
	ds_read_b128 v[212:215], v179 offset:36864
	ds_read_b128 v[220:223], v179 offset:37888
	ds_read_b128 v[224:227], v179 offset:38912
	ds_read_b128 v[228:231], v179 offset:39936
	s_add_u32 vcc_lo, s42, 0x100000
	s_addc_u32 vcc_hi, s43, 0
	s_add_i32 m0, s24, 0x4000
	s_nop 0
	global_load_lds_dwordx4 v146, vcc
	s_add_i32 m0, s24, 0x6000
	s_nop 0
	global_load_lds_dwordx4 v150, vcc
	s_sleep 2
	s_waitcnt lgkmcnt(0)
	s_waitcnt vmcnt(8)
	s_barrier
; #define PG8_STAGE(bufoff, gbase, voff) do { _Pragma("unroll") for (int _i = 0; _i < 2; ++_i) \
;         __builtin_amdgcn_global_load_lds((const unsigned*)((const char*)(gbase) + (voff)[_i]), (PG8_LAS unsigned*)(lds + (bufoff) + ldsw + _i * 8192), 16, 0, 0); } while (0)
; #define PG8_LDA(dst, b, h) do { _Pragma("unroll") for (int m = 0; m < 4; ++m) _Pragma("unroll") for (int k = 0; k < 2; ++k) dst[m][k] = *(const PG8_LAS bf16x8*)(lds + PG8_SA(b, h) + aoff + m * 2048 + k * 1024); } while (0)
; #define PG8_LDB(dst, b, h) do { _Pragma("unroll") for (int n = 0; n < 2; ++n) _Pragma("unroll") for (int k = 0; k < 2; ++k) dst[n][k] = *(const PG8_LAS bf16x8*)(lds + PG8_SB(b, h) + boff + n * 2048 + k * 1024); } while (0)
; #define PG8_MMA(ai, bj, At, Bt) do { __builtin_amdgcn_s_setprio(1); _Pragma("unroll") for (int m = 0; m < 4; ++m) _Pragma("unroll") for (int n = 0; n < 2; ++n) _Pragma("unroll") for (int k = 0; k < 2; ++k) \
;         acc[ai][bj][m][n] = __builtin_amdgcn_mfma_f32_16x16x32_bf16(Bt[n][k], At[m][k], acc[ai][bj][m][n], 0, 0, 0); __builtin_amdgcn_s_setprio(0); } while (0)
; #define PG8_WAIT_V(n) asm volatile("s_waitcnt vmcnt(" #n ")" ::: "memory")
; #define PG8_WAIT_L(n) asm volatile("s_waitcnt lgkmcnt(" #n ")" ::: "memory")
; #define PG8_BAR __builtin_amdgcn_s_barrier()
; #define PG8_SCHED __builtin_amdgcn_sched_barrier(0)
; template <class Epi, class Sched, bool ALIGN_EPI = false, bool SP2 = false>
; __device__ __forceinline__ void gemm_phase(PG8_LAS unsigned char* lds, const Gemm g, const Sched& S, const Epi& E) {
;     ...
;             PG8_LDB(B0, 1, 0); PG8_LDB(B1, 1, 1); PG8_SCHED; PG8_LDA(At, 1, 0); PG8_STAGE(PG8_SA(0, 1), a2 + hstep, voffA);
;             PG8_WAIT_V(8); PG8_WAIT_L(0); PG8_BAR; PG8_MMA(0, 0, At, B0); PG8_MMA(0, 1, At, B1); PG8_BAR; PG8_SCHED;
;             PG8_LDA(At, 1, 1); PG8_STAGE(PG8_SB(1, 0), b3, voffB); PG8_STAGE(PG8_SB(1, 1), b3 + hstep, voffB); PG8_STAGE(PG8_SA(1, 0), a3, voffA);
;             PG8_WAIT_V(8); PG8_WAIT_L(0); PG8_BAR; PG8_MMA(1, 0, At, B0); PG8_MMA(1, 1, At, B1); PG8_BAR; PG8_SCHED;
	s_setprio 2
	v_mfma_f32_16x16x32_bf16 v[126:129], v[130:133], v[196:199], v[126:129]
	v_mfma_f32_16x16x32_bf16 v[122:125], v[138:141], v[196:199], v[122:125]
	v_mfma_f32_16x16x32_bf16 v[110:113], v[130:133], v[204:207], v[110:113]
	v_mfma_f32_16x16x32_bf16 v[106:109], v[138:141], v[204:207], v[106:109]
	v_mfma_f32_16x16x32_bf16 v[94:97], v[130:133], v[212:215], v[94:97]
	v_mfma_f32_16x16x32_bf16 v[90:93], v[138:141], v[212:215], v[90:93]
	v_mfma_f32_16x16x32_bf16 v[78:81], v[130:133], v[224:227], v[78:81]
	v_mfma_f32_16x16x32_bf16 v[74:77], v[138:141], v[224:227], v[74:77]
	v_mfma_f32_16x16x32_bf16 v[126:129], v[134:137], v[200:203], v[126:129]
	v_mfma_f32_16x16x32_bf16 v[122:125], v[142:145], v[200:203], v[122:125]
	v_mfma_f32_16x16x32_bf16 v[110:113], v[134:137], v[208:211], v[110:113]
	v_mfma_f32_16x16x32_bf16 v[106:109], v[142:145], v[208:211], v[106:109]
	v_mfma_f32_16x16x32_bf16 v[94:97], v[134:137], v[220:223], v[94:97]
	v_mfma_f32_16x16x32_bf16 v[90:93], v[142:145], v[220:223], v[90:93]
	v_mfma_f32_16x16x32_bf16 v[78:81], v[134:137], v[228:231], v[78:81]
	v_mfma_f32_16x16x32_bf16 v[74:77], v[142:145], v[228:231], v[74:77]
	v_mfma_f32_16x16x32_bf16 v[118:121], v[162:165], v[196:199], v[118:121]
	v_mfma_f32_16x16x32_bf16 v[114:117], v[184:187], v[196:199], v[114:117]
	v_mfma_f32_16x16x32_bf16 v[102:105], v[162:165], v[204:207], v[102:105]
	v_mfma_f32_16x16x32_bf16 v[98:101], v[184:187], v[204:207], v[98:101]
	v_mfma_f32_16x16x32_bf16 v[86:89], v[162:165], v[212:215], v[86:89]
	v_mfma_f32_16x16x32_bf16 v[82:85], v[184:187], v[212:215], v[82:85]
	v_mfma_f32_16x16x32_bf16 v[70:73], v[162:165], v[224:227], v[70:73]
	v_mfma_f32_16x16x32_bf16 v[66:69], v[184:187], v[224:227], v[66:69]
	v_mfma_f32_16x16x32_bf16 v[118:121], v[180:183], v[200:203], v[118:121]
	v_mfma_f32_16x16x32_bf16 v[114:117], v[188:191], v[200:203], v[114:117]
	v_mfma_f32_16x16x32_bf16 v[102:105], v[180:183], v[208:211], v[102:105]
	v_mfma_f32_16x16x32_bf16 v[98:101], v[188:191], v[208:211], v[98:101]
	v_mfma_f32_16x16x32_bf16 v[86:89], v[180:183], v[220:223], v[86:89]
	v_mfma_f32_16x16x32_bf16 v[82:85], v[188:191], v[220:223], v[82:85]
	v_mfma_f32_16x16x32_bf16 v[70:73], v[180:183], v[228:231], v[70:73]
	v_mfma_f32_16x16x32_bf16 v[66:69], v[188:191], v[228:231], v[66:69]
	s_setprio 0
	ds_read_b128 v[196:199], v179 offset:49152
	ds_read_b128 v[200:203], v179 offset:50176
	ds_read_b128 v[204:207], v179 offset:51200
	ds_read_b128 v[208:211], v179 offset:52224
	ds_read_b128 v[212:215], v179 offset:53248
	ds_read_b128 v[220:223], v179 offset:54272
	ds_read_b128 v[224:227], v179 offset:55296
	ds_read_b128 v[228:231], v179 offset:56320
	s_add_u32 s60, s40, 0x80
	s_addc_u32 s61, s41, 0
	s_add_u32 vcc_lo, s60, 0x100000
	s_addc_u32 vcc_hi, s61, 0
	s_add_i32 m0, s24, 0x18000
	s_nop 0
	global_load_lds_dwordx4 v148, s[60:61]
	s_add_i32 m0, s24, 0x1a000
	s_nop 0
	global_load_lds_dwordx4 v152, s[60:61]
	s_add_i32 m0, s24, 0x1c000
	s_nop 0
	global_load_lds_dwordx4 v148, vcc
	s_add_i32 m0, s24, 0x1e000
	s_nop 0
	global_load_lds_dwordx4 v152, vcc
	s_add_u32 s60, s42, 0x80
	s_addc_u32 s61, s43, 0
	s_add_i32 m0, s24, 0x8000
	s_nop 0
	global_load_lds_dwordx4 v146, s[60:61]
	s_add_i32 m0, s24, 0xa000
	s_nop 0
	global_load_lds_dwordx4 v150, s[60:61]
	s_sleep 2
	s_waitcnt lgkmcnt(0)
	s_waitcnt vmcnt(8)
	s_barrier
	s_setprio 2
	v_mfma_f32_16x16x32_bf16 v[62:65], v[130:133], v[196:199], v[62:65]
	v_mfma_f32_16x16x32_bf16 v[58:61], v[138:141], v[196:199], v[58:61]
	v_mfma_f32_16x16x32_bf16 v[46:49], v[130:133], v[204:207], v[46:49]
	v_mfma_f32_16x16x32_bf16 v[42:45], v[138:141], v[204:207], v[42:45]
	v_mfma_f32_16x16x32_bf16 v[30:33], v[130:133], v[212:215], v[30:33]
	v_mfma_f32_16x16x32_bf16 v[26:29], v[138:141], v[212:215], v[26:29]
	v_mfma_f32_16x16x32_bf16 v[14:17], v[130:133], v[224:227], v[14:17]
	v_mfma_f32_16x16x32_bf16 v[10:13], v[138:141], v[224:227], v[10:13]
	v_mfma_f32_16x16x32_bf16 v[62:65], v[134:137], v[200:203], v[62:65]
	v_mfma_f32_16x16x32_bf16 v[58:61], v[142:145], v[200:203], v[58:61]
	v_mfma_f32_16x16x32_bf16 v[46:49], v[134:137], v[208:211], v[46:49]
	v_mfma_f32_16x16x32_bf16 v[42:45], v[142:145], v[208:211], v[42:45]
	v_mfma_f32_16x16x32_bf16 v[30:33], v[134:137], v[220:223], v[30:33]
	v_mfma_f32_16x16x32_bf16 v[26:29], v[142:145], v[220:223], v[26:29]
	v_mfma_f32_16x16x32_bf16 v[14:17], v[134:137], v[228:231], v[14:17]
	v_mfma_f32_16x16x32_bf16 v[10:13], v[142:145], v[228:231], v[10:13]
	v_mfma_f32_16x16x32_bf16 v[54:57], v[162:165], v[196:199], v[54:57]
	v_mfma_f32_16x16x32_bf16 v[50:53], v[184:187], v[196:199], v[50:53]
	v_mfma_f32_16x16x32_bf16 v[38:41], v[162:165], v[204:207], v[38:41]
	v_mfma_f32_16x16x32_bf16 v[34:37], v[184:187], v[204:207], v[34:37]
	v_mfma_f32_16x16x32_bf16 v[22:25], v[162:165], v[212:215], v[22:25]
	v_mfma_f32_16x16x32_bf16 v[18:21], v[184:187], v[212:215], v[18:21]
	v_mfma_f32_16x16x32_bf16 v[6:9], v[162:165], v[224:227], v[6:9]
	v_mfma_f32_16x16x32_bf16 v[2:5], v[184:187], v[224:227], v[2:5]
	v_mfma_f32_16x16x32_bf16 v[54:57], v[180:183], v[200:203], v[54:57]
	v_mfma_f32_16x16x32_bf16 v[50:53], v[188:191], v[200:203], v[50:53]
	v_mfma_f32_16x16x32_bf16 v[38:41], v[180:183], v[208:211], v[38:41]
	v_mfma_f32_16x16x32_bf16 v[34:37], v[188:191], v[208:211], v[34:37]
	v_mfma_f32_16x16x32_bf16 v[22:25], v[180:183], v[220:223], v[22:25]
	v_mfma_f32_16x16x32_bf16 v[18:21], v[188:191], v[220:223], v[18:21]
	v_mfma_f32_16x16x32_bf16 v[6:9], v[180:183], v[228:231], v[6:9]
	v_mfma_f32_16x16x32_bf16 v[2:5], v[188:191], v[228:231], v[2:5]
	s_setprio 0
	s_add_i32 s58, s58, 2
	s_add_u32 s36, s36, 0x100
	s_addc_u32 s37, s37, 0
	s_add_u32 s56, s56, 0x100
	s_addc_u32 s57, s57, 0
	s_cmp_gt_u32 s58, 61
	s_cbranch_scc0 .Lf1_h1

;     __device__ __forceinline__ bool next(int i, Unit& u) const { const long L = (long)i * G + c; if (L >= nwg) return false; std_map((int)L, nM, nN, u, wgm); u.ui = i; return true; }
;     __device__ __forceinline__ bool next(int i, Unit& u) const { if (i >= 4) return false; const int x = c & 7, r = c >> 3; u.pm = 16 * i + 4 * (x >> 1) + (r & 3); u.pn = 8 * (x & 1) + (r >> 2); u.ui = i; return true; }
; #define PG8_BAR __builtin_amdgcn_s_barrier()
; template <class Epi, class Sched, bool ALIGN_EPI = false, bool SP2 = false>
; __device__ __forceinline__ void gemm_phase(PG8_LAS unsigned char* lds, const Gemm g, const Sched& S, const Epi& E) {
;     const int tid = threadIdx.x, wid = __builtin_amdgcn_readfirstlane(tid >> 6), lane = tid & 63, wr = wid >> 2, wc = wid & 3, fr = lane & 15, fq = lane >> 4;
;     const int K = g.K, nt = K / BK;
;     unsigned voffA[2], voffB[2];
; #pragma unroll
;     for (int i = 0; i < 2; ++i) { int R, C; stage_rc(tid * 16 + i * 8192, R, C); const int Rb = Epi::PERM ? ((R & ~31) + perm32(R & 31)) : R;
;         voffA[i] = (unsigned)(R * g.ld + C) * 2u; voffB[i] = (unsigned)(Rb * g.ld + C) * 2u; }
;     const size_t kstep = (size_t)(BK * 2);
;     const size_t hstep = (size_t)HALF * g.ld * 2;
;     const size_t tstep = 2 * hstep;
;     const unsigned ldsw = (unsigned)wid * 1024u;
;     const int aoff = lds_byte(wr * 64 + fr, fq * 8), boff = lds_byte(wc * 32 + fr, fq * 8);
;     ...
;     Unit cur, nxt; int ui = 0;
;     if (!S.next(0, cur)) return;
;     f32x4 acc[2][2][4][2];
; #pragma unroll
;     for (int a = 0; a < 2; ++a)
; #pragma unroll
;         for (int b = 0; b < 2; ++b)
; #pragma unroll
;             for (int m = 0; m < 4; ++m)
; #pragma unroll
;                 for (int n = 0; n < 2; ++n) acc[a][b][m][n] = (f32x4){0.f, 0.f, 0.f, 0.f};
;     bf16x8 At[4][2], B0[2][2], B1[2][2];
;     const char* cA; const char* cB; S.bases(cur, g, tstep, cA, cB);
;     S.a_ready(cur);
;     if constexpr (SP2) {
;         PG8_STAGE(PG8_SB(0, 0), cB, voffB); PG8_STAGE(PG8_SB(0, 1), cB + hstep, voffB); PG8_STAGE(PG8_SA(0, 0), cA, voffA); PG8_STAGE(PG8_SA(0, 1), cA + hstep, voffA);
;         if (wr == 1) PG8_BAR;
;         PG8_WAIT_V(2); PG8_BAR;
;         PG8_STAGE(PG8_SB(1, 0), cB + kstep, voffB); PG8_STAGE(PG8_SA(1, 0), cA + kstep, voffA); PG8_STAGE(PG8_SB(1, 1), cB + hstep + kstep, voffB);
;         PG8_WAIT_V(6); PG8_BAR;
.LBB0_1315:
	s_or_b64 exec, exec, s[4:5]
	v_lshrrev_b32_e32 v6, 1, v0
	v_and_b32_e32 v13, 24, v6
	v_lshrrev_b32_e32 v6, 5, v0
	v_and_b32_e32 v1, 32, v0
	v_and_b32_e32 v6, 4, v6
	v_bfe_u32 v7, v0, 2, 2
	v_bfe_u32 v4, v0, 2, 4
	v_bitop3_b32 v1, v194, v1, 48 bitop3:0x6c
	v_and_b32_e32 v3, 64, v0
	v_or3_b32 v6, v6, v7, v13
	v_lshrrev_b32_e32 v7, 3, v0
	v_or_b32_e32 v5, v1, v3
	v_and_or_b32 v8, v7, 48, v4
	v_and_or_b32 v7, v7, 32, v6
	v_lshrrev_b32_e32 v5, 1, v5
	v_mul_u32_u24_e32 v7, 0x4040, v7
	v_or_b32_e32 v7, v7, v5
	v_lshlrev_b32_e32 v138, 1, v7
	v_bfe_u32 v7, v0, 3, 25
	v_or_b32_e32 v7, 64, v7
	s_movk_i32 s2, 0x70
	v_and_or_b32 v4, v7, s2, v4
	s_movk_i32 s2, 0x60
	v_readfirstlane_b32 s14, v0
	v_and_or_b32 v6, v7, s2, v6
	s_lshl_b32 s2, s85, 1
	s_lshr_b32 s12, s14, 6
	s_bfe_u32 s4, s85, 0x20003
	s_and_b32 s2, s2, 12
	s_lshr_b32 s15, s14, 8
	s_lshl_b32 s17, s12, 10
	s_or_b32 s2, s2, s4
	s_mul_hi_i32 s5, s6, 0x808000
	s_mul_i32 s6, s6, 0x808000
	v_mul_u32_u24_e32 v14, 0x4040, v4
	s_add_u32 s4, s28, s6
	v_or_b32_e32 v4, v14, v5
	s_addc_u32 s5, s29, s5
	s_add_i32 s24, s17, 0
	v_lshlrev_b32_e32 v140, 1, v4
	v_mul_u32_u24_e32 v4, 0x4040, v6
	s_add_i32 m0, s24, 0x10000
	s_waitcnt lgkmcnt(0)
	s_barrier
	v_or_b32_e32 v4, v4, v5
	global_load_lds_dwordx4 v138, s[4:5]
	s_add_i32 m0, s24, 0x12000
	v_lshlrev_b32_e32 v142, 1, v4
	s_add_u32 s6, s4, 0x404000
	global_load_lds_dwordx4 v142, s[4:5]
	s_addc_u32 s7, s5, 0
	s_add_i32 m0, s24, 0x14000
	s_mul_i32 s10, s2, 0x808000
	global_load_lds_dwordx4 v138, s[6:7]
	s_add_i32 m0, s24, 0x16000
	v_mul_u32_u24_e32 v12, 0x4040, v8
	global_load_lds_dwordx4 v142, s[6:7]
	s_add_u32 s6, s44, s10
	v_or_b32_e32 v8, v5, v12
	s_addc_u32 s7, s45, 0
	s_add_i32 s25, s24, 0x2000
	v_lshlrev_b32_e32 v136, 1, v8
	s_mov_b32 m0, s24
	s_add_u32 s10, s6, 0x404000
	global_load_lds_dwordx4 v136, s[6:7]
	s_mov_b32 m0, s25
	s_addc_u32 s11, s7, 0
	s_add_i32 s26, s24, 0x4000
	global_load_lds_dwordx4 v140, s[6:7]
	s_mov_b32 m0, s26
	s_add_i32 s27, s24, 0x6000
	global_load_lds_dwordx4 v136, s[10:11]
	s_mov_b32 m0, s27
	v_mov_b32_e32 v139, 0
	global_load_lds_dwordx4 v140, s[10:11]
	v_mov_b32_e32 v143, v139
	v_mov_b32_e32 v137, v139
	v_mov_b32_e32 v141, v139
	s_cmp_eq_u32 s15, 1
	s_mov_b32 s28, 0
	v_lshl_add_u64 v[10:11], s[4:5], 0, v[138:139]
	v_lshl_add_u64 v[8:9], s[4:5], 0, v[142:143]
	v_lshl_add_u64 v[4:5], s[6:7], 0, v[136:137]
	s_cselect_b64 s[10:11], -1, 0
	s_cmp_lg_u32 s15, 1
	v_lshl_add_u64 v[6:7], s[6:7], 0, v[140:141]
	s_cbranch_scc1 .LBB0_1317
.LBB0_1317:
	s_lshl_b32 s12, s12, 5
	s_and_b32 s21, s12, 0x60
	s_mov_b64 s[12:13], 0x80
	s_add_i32 m0, s24, 0x18000
	v_lshl_add_u64 v[10:11], v[10:11], 0, s[12:13]
	s_lshl_b32 s20, s15, 13
	s_lshl_b32 s22, s21, 7
	s_waitcnt vmcnt(2)
	s_barrier
	global_load_lds_dwordx4 v[10:11], off
	v_lshl_add_u64 v[8:9], v[8:9], 0, s[12:13]
	s_add_i32 m0, s24, 0x1a000
	s_add_i32 s29, s24, 0x8000
	s_add_i32 s30, s24, 0xa000
	global_load_lds_dwordx4 v[8:9], off
	v_lshl_add_u64 v[4:5], v[4:5], 0, s[12:13]
	s_mov_b32 m0, s29
	s_add_u32 s18, s4, 0x404080
	global_load_lds_dwordx4 v[4:5], off
	v_lshl_add_u64 v[4:5], v[6:7], 0, s[12:13]
	s_mov_b32 m0, s30
	s_addc_u32 s19, s5, 0
	global_load_lds_dwordx4 v[4:5], off
	s_add_i32 m0, s24, 0x1c000
	v_lshl_add_u64 v[4:5], s[18:19], 0, v[138:139]
	global_load_lds_dwordx4 v[4:5], off
	v_lshl_add_u64 v[4:5], s[18:19], 0, v[142:143]
	s_add_i32 m0, s24, 0x1e000
	v_lshl_or_b32 v154, s15, 6, v195
	global_load_lds_dwordx4 v[4:5], off
	v_lshlrev_b32_e32 v4, 1, v13
	v_lshlrev_b32_e32 v0, 6, v0
	s_movk_i32 s15, 0x3c0
	s_cmpk_lt_u32 s14, 0x100
	v_lshl_or_b32 v5, v195, 6, v4
	v_and_or_b32 v0, v0, s15, v4
	v_and_b32_e32 v2, 32, v2
	s_cselect_b64 s[14:15], -1, 0
	v_or_b32_e32 v4, s21, v13
	s_add_i32 s18, 0, 0x20800
	v_bitop3_b32 v0, s22, v0, v2 bitop3:0xf6
	s_waitcnt vmcnt(6)
	v_lshl_add_u32 v155, v4, 2, s18
	v_or_b32_e32 v4, s16, v4
	v_add_u16_e32 v1, v1, v3
	s_add_i32 s35, 0, 0x10000
	s_add_i32 s37, 0, 0x14000
	s_add_i32 s50, 0, 0x18000
	s_add_i32 s52, 0, 0x1c000
	v_bitop3_b32 v2, v5, s20, v2 bitop3:0xde
	v_ashrrev_i32_e32 v5, 31, v4
	v_lshrrev_b16_e32 v1, 1, v1
	v_add_u32_e32 v156, s35, v0
	v_add_u32_e32 v157, s37, v0
	s_add_i32 s35, s35, s17
	s_add_i32 s37, s37, s17
	v_add_u32_e32 v159, s50, v0
	v_add_u32_e32 v160, s52, v0
	s_add_i32 s50, s50, s17
	s_add_i32 s52, s52, s17
	v_lshl_add_u64 v[144:145], v[4:5], 1, s[8:9]
	v_add_lshl_u32 v146, v12, v1, 1
	v_mov_b32_e32 v147, v139
	v_add_lshl_u32 v148, v14, v1, 1
	v_mov_b32_e32 v149, v139
	v_add_u32_e32 v158, 0, v2
	s_add_i32 s31, s24, 0xc000
	s_add_i32 s34, s24, 0xe000
	s_add_i32 s36, s35, 0x2000
	s_add_i32 s40, s37, 0x2000
	s_mov_b32 s41, 0x20000
	s_mov_b32 s42, 0x40000
	s_mov_b32 s43, 0x60000
	s_mov_b32 s46, 0x100000
	s_mov_b32 s47, 0x120000
	s_mov_b32 s48, 0x140000
	s_mov_b32 s49, 0x160000
	s_add_i32 s51, s50, 0x2000
	s_add_i32 s53, s52, 0x2000
	s_mov_b32 s54, s2
	s_mov_b64 s[16:17], s[4:5]
	s_barrier
	s_branch .LBB0_1320

; #define PG8_STAGE(bufoff, gbase, voff) do { _Pragma("unroll") for (int _i = 0; _i < 2; ++_i) \
;         __builtin_amdgcn_global_load_lds((const unsigned*)((const char*)(gbase) + (voff)[_i]), (PG8_LAS unsigned*)(lds + (bufoff) + ldsw + _i * 8192), 16, 0, 0); } while (0)
; #define PG8_LDA(dst, b, h) do { _Pragma("unroll") for (int m = 0; m < 4; ++m) _Pragma("unroll") for (int k = 0; k < 2; ++k) dst[m][k] = *(const PG8_LAS bf16x8*)(lds + PG8_SA(b, h) + aoff + m * 2048 + k * 1024); } while (0)
; #define PG8_LDB(dst, b, h) do { _Pragma("unroll") for (int n = 0; n < 2; ++n) _Pragma("unroll") for (int k = 0; k < 2; ++k) dst[n][k] = *(const PG8_LAS bf16x8*)(lds + PG8_SB(b, h) + boff + n * 2048 + k * 1024); } while (0)
; #define PG8_MMA(ai, bj, At, Bt) do { __builtin_amdgcn_s_setprio(1); _Pragma("unroll") for (int m = 0; m < 4; ++m) _Pragma("unroll") for (int n = 0; n < 2; ++n) _Pragma("unroll") for (int k = 0; k < 2; ++k) \
;         acc[ai][bj][m][n] = __builtin_amdgcn_mfma_f32_16x16x32_bf16(Bt[n][k], At[m][k], acc[ai][bj][m][n], 0, 0, 0); __builtin_amdgcn_s_setprio(0); } while (0)
; #define PG8_WAIT_V(n) asm volatile("s_waitcnt vmcnt(" #n ")" ::: "memory")
; #define PG8_WAIT_L(n) asm volatile("s_waitcnt lgkmcnt(" #n ")" ::: "memory")
; #define PG8_BAR __builtin_amdgcn_s_barrier()
; #define PG8_SCHED __builtin_amdgcn_sched_barrier(0)
; template <class Epi, class Sched, bool ALIGN_EPI = false, bool SP2 = false>
; __device__ __forceinline__ void gemm_phase(PG8_LAS unsigned char* lds, const Gemm g, const Sched& S, const Epi& E) {
;     ...
;             PG8_LDB(B0, 0, 0); PG8_LDB(B1, 0, 1); PG8_SCHED; PG8_LDA(At, 0, 0); PG8_STAGE(PG8_SA(1, 1), a1 + hstep, voffA);
;             PG8_WAIT_V(8); PG8_WAIT_L(0); PG8_BAR; PG8_MMA(0, 0, At, B0); PG8_MMA(0, 1, At, B1); PG8_BAR; PG8_SCHED;
;             PG8_LDA(At, 0, 1); PG8_STAGE(PG8_SB(0, 0), b2, voffB); PG8_STAGE(PG8_SB(0, 1), b2 + hstep, voffB); PG8_STAGE(PG8_SA(0, 0), a2, voffA);
;             PG8_WAIT_V(8); PG8_WAIT_L(0); PG8_BAR; PG8_MMA(1, 0, At, B0); PG8_MMA(1, 1, At, B1); PG8_BAR; PG8_SCHED;
.LBB0_1321:
	ds_read_b128 v[128:131], v156
	ds_read_b128 v[132:135], v156 offset:1024
	ds_read_b128 v[150:153], v156 offset:2048
	ds_read_b128 v[162:165], v156 offset:3072
	ds_read_b128 v[166:169], v157
	ds_read_b128 v[170:173], v157 offset:1024
	ds_read_b128 v[174:177], v157 offset:2048
	ds_read_b128 v[178:181], v157 offset:3072
	s_add_u32 s20, s18, 0xffbfc080
	s_addc_u32 s21, s19, -1
	s_cmpk_eq_i32 s59, 0xfc
	s_cselect_b32 s23, s7, s21
	s_cselect_b32 s22, s6, s20
	s_cselect_b32 s21, s17, s58
	s_cselect_b32 s20, s16, s57
	ds_read_b128 v[182:185], v158
	ds_read_b128 v[186:189], v158 offset:1024
	ds_read_b128 v[190:193], v158 offset:2048
	ds_read_b128 v[194:197], v158 offset:3072
	ds_read_b128 v[198:201], v158 offset:4096
	ds_read_b128 v[202:205], v158 offset:5120
	ds_read_b128 v[206:209], v158 offset:6144
	ds_read_b128 v[210:213], v158 offset:7168
	s_add_i32 m0, s24, 0xc000
	s_nop 0
	global_load_lds_dwordx4 v136, s[18:19]
	s_add_i32 m0, s24, 0xe000
	s_nop 0
	global_load_lds_dwordx4 v140, s[18:19]
	s_waitcnt lgkmcnt(0)
	s_setprio 1
	v_mfma_f32_16x16x32_bf16 v[124:127], v[128:131], v[182:185], v[124:127]
	v_mfma_f32_16x16x32_bf16 v[120:123], v[150:153], v[182:185], v[120:123]
	v_mfma_f32_16x16x32_bf16 v[116:119], v[128:131], v[190:193], v[116:119]
	v_mfma_f32_16x16x32_bf16 v[112:115], v[150:153], v[190:193], v[112:115]
	v_mfma_f32_16x16x32_bf16 v[108:111], v[128:131], v[198:201], v[108:111]
	v_mfma_f32_16x16x32_bf16 v[104:107], v[150:153], v[198:201], v[104:107]
	v_mfma_f32_16x16x32_bf16 v[100:103], v[128:131], v[206:209], v[100:103]
	v_mfma_f32_16x16x32_bf16 v[96:99], v[150:153], v[206:209], v[96:99]
	v_mfma_f32_16x16x32_bf16 v[124:127], v[132:135], v[186:189], v[124:127]
	v_mfma_f32_16x16x32_bf16 v[120:123], v[162:165], v[186:189], v[120:123]
	v_mfma_f32_16x16x32_bf16 v[116:119], v[132:135], v[194:197], v[116:119]
	v_mfma_f32_16x16x32_bf16 v[112:115], v[162:165], v[194:197], v[112:115]
	v_mfma_f32_16x16x32_bf16 v[108:111], v[132:135], v[202:205], v[108:111]
	v_mfma_f32_16x16x32_bf16 v[104:107], v[162:165], v[202:205], v[104:107]
	v_mfma_f32_16x16x32_bf16 v[100:103], v[132:135], v[210:213], v[100:103]
	v_mfma_f32_16x16x32_bf16 v[96:99], v[162:165], v[210:213], v[96:99]
	v_mfma_f32_16x16x32_bf16 v[68:71], v[166:169], v[182:185], v[68:71]
	v_mfma_f32_16x16x32_bf16 v[64:67], v[174:177], v[182:185], v[64:67]
	v_mfma_f32_16x16x32_bf16 v[52:55], v[166:169], v[190:193], v[52:55]
	v_mfma_f32_16x16x32_bf16 v[48:51], v[174:177], v[190:193], v[48:51]
	v_mfma_f32_16x16x32_bf16 v[44:47], v[166:169], v[198:201], v[44:47]
	v_mfma_f32_16x16x32_bf16 v[40:43], v[174:177], v[198:201], v[40:43]
	v_mfma_f32_16x16x32_bf16 v[36:39], v[166:169], v[206:209], v[36:39]
	v_mfma_f32_16x16x32_bf16 v[32:35], v[174:177], v[206:209], v[32:35]
	v_mfma_f32_16x16x32_bf16 v[68:71], v[170:173], v[186:189], v[68:71]
	v_mfma_f32_16x16x32_bf16 v[64:67], v[178:181], v[186:189], v[64:67]
	v_mfma_f32_16x16x32_bf16 v[52:55], v[170:173], v[194:197], v[52:55]
	v_mfma_f32_16x16x32_bf16 v[48:51], v[178:181], v[194:197], v[48:51]
	v_mfma_f32_16x16x32_bf16 v[44:47], v[170:173], v[202:205], v[44:47]
	v_mfma_f32_16x16x32_bf16 v[40:43], v[178:181], v[202:205], v[40:43]
	v_mfma_f32_16x16x32_bf16 v[36:39], v[170:173], v[210:213], v[36:39]
	v_mfma_f32_16x16x32_bf16 v[32:35], v[178:181], v[210:213], v[32:35]
	s_setprio 0
	s_waitcnt vmcnt(8)
	s_barrier
	ds_read_b128 v[182:185], v158 offset:16384
	ds_read_b128 v[186:189], v158 offset:17408
	ds_read_b128 v[190:193], v158 offset:18432
	ds_read_b128 v[194:197], v158 offset:19456
	ds_read_b128 v[198:201], v158 offset:20480
	ds_read_b128 v[202:205], v158 offset:21504
	ds_read_b128 v[206:209], v158 offset:22528
	ds_read_b128 v[210:213], v158 offset:23552
	s_add_u32 vcc_lo, s20, 0x404000
	s_addc_u32 vcc_hi, s21, 0
	s_add_i32 m0, s24, 0x10000
	s_nop 0
	global_load_lds_dwordx4 v138, s[20:21]
	s_add_i32 m0, s24, 0x12000
	s_nop 0
	global_load_lds_dwordx4 v142, s[20:21]
	s_add_i32 m0, s24, 0x14000
	s_nop 0
	global_load_lds_dwordx4 v138, vcc
	s_add_i32 m0, s24, 0x16000
	s_nop 0
	global_load_lds_dwordx4 v142, vcc
	s_mov_b32 m0, s24
	s_nop 0
	global_load_lds_dwordx4 v136, s[22:23]
	s_add_i32 m0, s24, 0x2000
	s_nop 0
	global_load_lds_dwordx4 v140, s[22:23]
	s_waitcnt lgkmcnt(0)
	s_setprio 1
	v_mfma_f32_16x16x32_bf16 v[92:95], v[128:131], v[182:185], v[92:95]
	v_mfma_f32_16x16x32_bf16 v[88:91], v[150:153], v[182:185], v[88:91]
	v_mfma_f32_16x16x32_bf16 v[84:87], v[128:131], v[190:193], v[84:87]
	v_mfma_f32_16x16x32_bf16 v[80:83], v[150:153], v[190:193], v[80:83]
	v_mfma_f32_16x16x32_bf16 v[76:79], v[128:131], v[198:201], v[76:79]
	v_mfma_f32_16x16x32_bf16 v[72:75], v[150:153], v[198:201], v[72:75]
	v_mfma_f32_16x16x32_bf16 v[60:63], v[128:131], v[206:209], v[60:63]
	v_mfma_f32_16x16x32_bf16 v[56:59], v[150:153], v[206:209], v[56:59]
	v_mfma_f32_16x16x32_bf16 v[92:95], v[132:135], v[186:189], v[92:95]
	v_mfma_f32_16x16x32_bf16 v[88:91], v[162:165], v[186:189], v[88:91]
	v_mfma_f32_16x16x32_bf16 v[84:87], v[132:135], v[194:197], v[84:87]
	v_mfma_f32_16x16x32_bf16 v[80:83], v[162:165], v[194:197], v[80:83]
	v_mfma_f32_16x16x32_bf16 v[76:79], v[132:135], v[202:205], v[76:79]
	v_mfma_f32_16x16x32_bf16 v[72:75], v[162:165], v[202:205], v[72:75]
	v_mfma_f32_16x16x32_bf16 v[60:63], v[132:135], v[210:213], v[60:63]
	v_mfma_f32_16x16x32_bf16 v[56:59], v[162:165], v[210:213], v[56:59]
	v_mfma_f32_16x16x32_bf16 v[28:31], v[166:169], v[182:185], v[28:31]
	v_mfma_f32_16x16x32_bf16 v[24:27], v[174:177], v[182:185], v[24:27]
	v_mfma_f32_16x16x32_bf16 v[20:23], v[166:169], v[190:193], v[20:23]
	v_mfma_f32_16x16x32_bf16 v[16:19], v[174:177], v[190:193], v[16:19]
	v_mfma_f32_16x16x32_bf16 v[12:15], v[166:169], v[198:201], v[12:15]
	v_mfma_f32_16x16x32_bf16 v[8:11], v[174:177], v[198:201], v[8:11]
	v_mfma_f32_16x16x32_bf16 v[4:7], v[166:169], v[206:209], v[4:7]
	v_mfma_f32_16x16x32_bf16 v[0:3], v[174:177], v[206:209], v[0:3]
	v_mfma_f32_16x16x32_bf16 v[28:31], v[170:173], v[186:189], v[28:31]
	v_mfma_f32_16x16x32_bf16 v[24:27], v[178:181], v[186:189], v[24:27]
	v_mfma_f32_16x16x32_bf16 v[20:23], v[170:173], v[194:197], v[20:23]
	v_mfma_f32_16x16x32_bf16 v[16:19], v[178:181], v[194:197], v[16:19]
	v_mfma_f32_16x16x32_bf16 v[12:15], v[170:173], v[202:205], v[12:15]
	v_mfma_f32_16x16x32_bf16 v[8:11], v[178:181], v[202:205], v[8:11]
	v_mfma_f32_16x16x32_bf16 v[4:7], v[170:173], v[210:213], v[4:7]
	v_mfma_f32_16x16x32_bf16 v[0:3], v[178:181], v[210:213], v[0:3]
	s_setprio 0
	s_waitcnt vmcnt(8)
	s_barrier
; #define PG8_STAGE(bufoff, gbase, voff) do { _Pragma("unroll") for (int _i = 0; _i < 2; ++_i) \
;         __builtin_amdgcn_global_load_lds((const unsigned*)((const char*)(gbase) + (voff)[_i]), (PG8_LAS unsigned*)(lds + (bufoff) + ldsw + _i * 8192), 16, 0, 0); } while (0)
; #define PG8_LDA(dst, b, h) do { _Pragma("unroll") for (int m = 0; m < 4; ++m) _Pragma("unroll") for (int k = 0; k < 2; ++k) dst[m][k] = *(const PG8_LAS bf16x8*)(lds + PG8_SA(b, h) + aoff + m * 2048 + k * 1024); } while (0)
; #define PG8_LDB(dst, b, h) do { _Pragma("unroll") for (int n = 0; n < 2; ++n) _Pragma("unroll") for (int k = 0; k < 2; ++k) dst[n][k] = *(const PG8_LAS bf16x8*)(lds + PG8_SB(b, h) + boff + n * 2048 + k * 1024); } while (0)
; #define PG8_MMA(ai, bj, At, Bt) do { __builtin_amdgcn_s_setprio(1); _Pragma("unroll") for (int m = 0; m < 4; ++m) _Pragma("unroll") for (int n = 0; n < 2; ++n) _Pragma("unroll") for (int k = 0; k < 2; ++k) \
;         acc[ai][bj][m][n] = __builtin_amdgcn_mfma_f32_16x16x32_bf16(Bt[n][k], At[m][k], acc[ai][bj][m][n], 0, 0, 0); __builtin_amdgcn_s_setprio(0); } while (0)
; #define PG8_WAIT_V(n) asm volatile("s_waitcnt vmcnt(" #n ")" ::: "memory")
; #define PG8_WAIT_L(n) asm volatile("s_waitcnt lgkmcnt(" #n ")" ::: "memory")
; #define PG8_BAR __builtin_amdgcn_s_barrier()
; #define PG8_SCHED __builtin_amdgcn_sched_barrier(0)
; template <class Epi, class Sched, bool ALIGN_EPI = false, bool SP2 = false>
; __device__ __forceinline__ void gemm_phase(PG8_LAS unsigned char* lds, const Gemm g, const Sched& S, const Epi& E) {
;     ...
;             PG8_LDB(B0, 1, 0); PG8_LDB(B1, 1, 1); PG8_SCHED; PG8_LDA(At, 1, 0); PG8_STAGE(PG8_SA(0, 1), a2 + hstep, voffA);
;             PG8_WAIT_V(8); PG8_WAIT_L(0); PG8_BAR; PG8_MMA(0, 0, At, B0); PG8_MMA(0, 1, At, B1); PG8_BAR; PG8_SCHED;
;             PG8_LDA(At, 1, 1); PG8_STAGE(PG8_SB(1, 0), b3, voffB); PG8_STAGE(PG8_SB(1, 1), b3 + hstep, voffB); PG8_STAGE(PG8_SA(1, 0), a3, voffA);
;             PG8_WAIT_V(8); PG8_WAIT_L(0); PG8_BAR; PG8_MMA(1, 0, At, B0); PG8_MMA(1, 1, At, B1); PG8_BAR; PG8_SCHED;
	ds_read_b128 v[128:131], v159
	ds_read_b128 v[132:135], v159 offset:1024
	ds_read_b128 v[150:153], v159 offset:2048
	ds_read_b128 v[162:165], v159 offset:3072
	ds_read_b128 v[166:169], v160
	ds_read_b128 v[170:173], v160 offset:1024
	ds_read_b128 v[174:177], v160 offset:2048
	ds_read_b128 v[178:181], v160 offset:3072
	ds_read_b128 v[182:185], v158 offset:32768
	ds_read_b128 v[186:189], v158 offset:33792
	ds_read_b128 v[190:193], v158 offset:34816
	ds_read_b128 v[194:197], v158 offset:35840
	ds_read_b128 v[198:201], v158 offset:36864
	ds_read_b128 v[202:205], v158 offset:37888
	ds_read_b128 v[206:209], v158 offset:38912
	ds_read_b128 v[210:213], v158 offset:39936
	s_add_u32 vcc_lo, s22, 0x404000
	s_addc_u32 vcc_hi, s23, 0
	s_add_i32 m0, s24, 0x4000
	s_nop 0
	global_load_lds_dwordx4 v136, vcc
	s_add_i32 m0, s24, 0x6000
	s_nop 0
	global_load_lds_dwordx4 v140, vcc
	s_waitcnt lgkmcnt(0)
	s_setprio 1
	v_mfma_f32_16x16x32_bf16 v[124:127], v[128:131], v[182:185], v[124:127]
	v_mfma_f32_16x16x32_bf16 v[120:123], v[150:153], v[182:185], v[120:123]
	v_mfma_f32_16x16x32_bf16 v[116:119], v[128:131], v[190:193], v[116:119]
	v_mfma_f32_16x16x32_bf16 v[112:115], v[150:153], v[190:193], v[112:115]
	v_mfma_f32_16x16x32_bf16 v[108:111], v[128:131], v[198:201], v[108:111]
	v_mfma_f32_16x16x32_bf16 v[104:107], v[150:153], v[198:201], v[104:107]
	v_mfma_f32_16x16x32_bf16 v[100:103], v[128:131], v[206:209], v[100:103]
	v_mfma_f32_16x16x32_bf16 v[96:99], v[150:153], v[206:209], v[96:99]
	v_mfma_f32_16x16x32_bf16 v[124:127], v[132:135], v[186:189], v[124:127]
	v_mfma_f32_16x16x32_bf16 v[120:123], v[162:165], v[186:189], v[120:123]
	v_mfma_f32_16x16x32_bf16 v[116:119], v[132:135], v[194:197], v[116:119]
	v_mfma_f32_16x16x32_bf16 v[112:115], v[162:165], v[194:197], v[112:115]
	v_mfma_f32_16x16x32_bf16 v[108:111], v[132:135], v[202:205], v[108:111]
	v_mfma_f32_16x16x32_bf16 v[104:107], v[162:165], v[202:205], v[104:107]
	v_mfma_f32_16x16x32_bf16 v[100:103], v[132:135], v[210:213], v[100:103]
	v_mfma_f32_16x16x32_bf16 v[96:99], v[162:165], v[210:213], v[96:99]
	v_mfma_f32_16x16x32_bf16 v[68:71], v[166:169], v[182:185], v[68:71]
	v_mfma_f32_16x16x32_bf16 v[64:67], v[174:177], v[182:185], v[64:67]
	v_mfma_f32_16x16x32_bf16 v[52:55], v[166:169], v[190:193], v[52:55]
	v_mfma_f32_16x16x32_bf16 v[48:51], v[174:177], v[190:193], v[48:51]
	v_mfma_f32_16x16x32_bf16 v[44:47], v[166:169], v[198:201], v[44:47]
	v_mfma_f32_16x16x32_bf16 v[40:43], v[174:177], v[198:201], v[40:43]
	v_mfma_f32_16x16x32_bf16 v[36:39], v[166:169], v[206:209], v[36:39]
	v_mfma_f32_16x16x32_bf16 v[32:35], v[174:177], v[206:209], v[32:35]
	v_mfma_f32_16x16x32_bf16 v[68:71], v[170:173], v[186:189], v[68:71]
	v_mfma_f32_16x16x32_bf16 v[64:67], v[178:181], v[186:189], v[64:67]
	v_mfma_f32_16x16x32_bf16 v[52:55], v[170:173], v[194:197], v[52:55]
	v_mfma_f32_16x16x32_bf16 v[48:51], v[178:181], v[194:197], v[48:51]
	v_mfma_f32_16x16x32_bf16 v[44:47], v[170:173], v[202:205], v[44:47]
	v_mfma_f32_16x16x32_bf16 v[40:43], v[178:181], v[202:205], v[40:43]
	v_mfma_f32_16x16x32_bf16 v[36:39], v[170:173], v[210:213], v[36:39]
	v_mfma_f32_16x16x32_bf16 v[32:35], v[178:181], v[210:213], v[32:35]
	s_setprio 0
	s_waitcnt vmcnt(8)
	s_barrier
	ds_read_b128 v[182:185], v158 offset:49152
	ds_read_b128 v[186:189], v158 offset:50176
	ds_read_b128 v[190:193], v158 offset:51200
	ds_read_b128 v[194:197], v158 offset:52224
	ds_read_b128 v[198:201], v158 offset:53248
	ds_read_b128 v[202:205], v158 offset:54272
	ds_read_b128 v[206:209], v158 offset:55296
	ds_read_b128 v[210:213], v158 offset:56320
	s_add_u32 s60, s20, 0x80
	s_addc_u32 s61, s21, 0
	s_add_u32 vcc_lo, s60, 0x404000
	s_addc_u32 vcc_hi, s61, 0
	s_add_i32 m0, s24, 0x18000
	s_nop 0
	global_load_lds_dwordx4 v138, s[60:61]
	s_add_i32 m0, s24, 0x1a000
	s_nop 0
	global_load_lds_dwordx4 v142, s[60:61]
	s_add_i32 m0, s24, 0x1c000
	s_nop 0
	global_load_lds_dwordx4 v138, vcc
	s_add_i32 m0, s24, 0x1e000
	s_nop 0
	global_load_lds_dwordx4 v142, vcc
	s_add_u32 s60, s22, 0x80
	s_addc_u32 s61, s23, 0
	s_add_i32 m0, s24, 0x8000
	s_nop 0
	global_load_lds_dwordx4 v136, s[60:61]
	s_add_i32 m0, s24, 0xa000
	s_nop 0
	global_load_lds_dwordx4 v140, s[60:61]
	s_waitcnt lgkmcnt(0)
	s_setprio 1
	v_mfma_f32_16x16x32_bf16 v[92:95], v[128:131], v[182:185], v[92:95]
	v_mfma_f32_16x16x32_bf16 v[88:91], v[150:153], v[182:185], v[88:91]
	v_mfma_f32_16x16x32_bf16 v[84:87], v[128:131], v[190:193], v[84:87]
	v_mfma_f32_16x16x32_bf16 v[80:83], v[150:153], v[190:193], v[80:83]
	v_mfma_f32_16x16x32_bf16 v[76:79], v[128:131], v[198:201], v[76:79]
	v_mfma_f32_16x16x32_bf16 v[72:75], v[150:153], v[198:201], v[72:75]
	v_mfma_f32_16x16x32_bf16 v[60:63], v[128:131], v[206:209], v[60:63]
	v_mfma_f32_16x16x32_bf16 v[56:59], v[150:153], v[206:209], v[56:59]
	v_mfma_f32_16x16x32_bf16 v[92:95], v[132:135], v[186:189], v[92:95]
	v_mfma_f32_16x16x32_bf16 v[88:91], v[162:165], v[186:189], v[88:91]
	v_mfma_f32_16x16x32_bf16 v[84:87], v[132:135], v[194:197], v[84:87]
	v_mfma_f32_16x16x32_bf16 v[80:83], v[162:165], v[194:197], v[80:83]
	v_mfma_f32_16x16x32_bf16 v[76:79], v[132:135], v[202:205], v[76:79]
	v_mfma_f32_16x16x32_bf16 v[72:75], v[162:165], v[202:205], v[72:75]
	v_mfma_f32_16x16x32_bf16 v[60:63], v[132:135], v[210:213], v[60:63]
	v_mfma_f32_16x16x32_bf16 v[56:59], v[162:165], v[210:213], v[56:59]
	v_mfma_f32_16x16x32_bf16 v[28:31], v[166:169], v[182:185], v[28:31]
	v_mfma_f32_16x16x32_bf16 v[24:27], v[174:177], v[182:185], v[24:27]
	v_mfma_f32_16x16x32_bf16 v[20:23], v[166:169], v[190:193], v[20:23]
	v_mfma_f32_16x16x32_bf16 v[16:19], v[174:177], v[190:193], v[16:19]
	v_mfma_f32_16x16x32_bf16 v[12:15], v[166:169], v[198:201], v[12:15]
	v_mfma_f32_16x16x32_bf16 v[8:11], v[174:177], v[198:201], v[8:11]
	v_mfma_f32_16x16x32_bf16 v[4:7], v[166:169], v[206:209], v[4:7]
	v_mfma_f32_16x16x32_bf16 v[0:3], v[174:177], v[206:209], v[0:3]
	v_mfma_f32_16x16x32_bf16 v[28:31], v[170:173], v[186:189], v[28:31]
	v_mfma_f32_16x16x32_bf16 v[24:27], v[178:181], v[186:189], v[24:27]
	v_mfma_f32_16x16x32_bf16 v[20:23], v[170:173], v[194:197], v[20:23]
	v_mfma_f32_16x16x32_bf16 v[16:19], v[178:181], v[194:197], v[16:19]
	v_mfma_f32_16x16x32_bf16 v[12:15], v[170:173], v[202:205], v[12:15]
	v_mfma_f32_16x16x32_bf16 v[8:11], v[178:181], v[202:205], v[8:11]
	v_mfma_f32_16x16x32_bf16 v[4:7], v[170:173], v[210:213], v[4:7]
	v_mfma_f32_16x16x32_bf16 v[0:3], v[178:181], v[210:213], v[0:3]
	s_setprio 0
	s_waitcnt vmcnt(8)
	s_barrier
	s_add_i32 s59, s59, 2
	s_add_u32 s18, s18, 0x100
	s_addc_u32 s19, s19, 0
	s_add_u32 s57, s57, 0x100
	s_addc_u32 s58, s58, 0
	s_cmpk_gt_u32 s59, 0xfd
	s_cbranch_scc0 .LBB0_1321
	s_branch .Lf2_exit
; #define PG8_STAGE(bufoff, gbase, voff) do { _Pragma("unroll") for (int _i = 0; _i < 2; ++_i) \
;         __builtin_amdgcn_global_load_lds((const unsigned*)((const char*)(gbase) + (voff)[_i]), (PG8_LAS unsigned*)(lds + (bufoff) + ldsw + _i * 8192), 16, 0, 0); } while (0)
; #define PG8_LDA(dst, b, h) do { _Pragma("unroll") for (int m = 0; m < 4; ++m) _Pragma("unroll") for (int k = 0; k < 2; ++k) dst[m][k] = *(const PG8_LAS bf16x8*)(lds + PG8_SA(b, h) + aoff + m * 2048 + k * 1024); } while (0)
; #define PG8_LDB(dst, b, h) do { _Pragma("unroll") for (int n = 0; n < 2; ++n) _Pragma("unroll") for (int k = 0; k < 2; ++k) dst[n][k] = *(const PG8_LAS bf16x8*)(lds + PG8_SB(b, h) + boff + n * 2048 + k * 1024); } while (0)
; #define PG8_MMA(ai, bj, At, Bt) do { __builtin_amdgcn_s_setprio(1); _Pragma("unroll") for (int m = 0; m < 4; ++m) _Pragma("unroll") for (int n = 0; n < 2; ++n) _Pragma("unroll") for (int k = 0; k < 2; ++k) \
;         acc[ai][bj][m][n] = __builtin_amdgcn_mfma_f32_16x16x32_bf16(Bt[n][k], At[m][k], acc[ai][bj][m][n], 0, 0, 0); __builtin_amdgcn_s_setprio(0); } while (0)
; #define PG8_WAIT_V(n) asm volatile("s_waitcnt vmcnt(" #n ")" ::: "memory")
; #define PG8_WAIT_L(n) asm volatile("s_waitcnt lgkmcnt(" #n ")" ::: "memory")
; #define PG8_BAR __builtin_amdgcn_s_barrier()
; #define PG8_SCHED __builtin_amdgcn_sched_barrier(0)
; template <class Epi, class Sched, bool ALIGN_EPI = false, bool SP2 = false>
; __device__ __forceinline__ void gemm_phase(PG8_LAS unsigned char* lds, const Gemm g, const Sched& S, const Epi& E) {
;     ...
;             PG8_LDB(B0, 0, 0); PG8_LDB(B1, 0, 1); PG8_SCHED; PG8_LDA(At, 0, 0); PG8_STAGE(PG8_SA(1, 1), a1 + hstep, voffA);
;             PG8_WAIT_V(8); PG8_WAIT_L(0); PG8_BAR; PG8_MMA(0, 0, At, B0); PG8_MMA(0, 1, At, B1); PG8_BAR; PG8_SCHED;
;             PG8_LDA(At, 0, 1); PG8_STAGE(PG8_SB(0, 0), b2, voffB); PG8_STAGE(PG8_SB(0, 1), b2 + hstep, voffB); PG8_STAGE(PG8_SA(0, 0), a2, voffA);
;             PG8_WAIT_V(8); PG8_WAIT_L(0); PG8_BAR; PG8_MMA(1, 0, At, B0); PG8_MMA(1, 1, At, B1); PG8_BAR; PG8_SCHED;
.Lf2_h1:
	ds_read_b128 v[128:131], v156
	ds_read_b128 v[132:135], v156 offset:1024
	ds_read_b128 v[150:153], v156 offset:2048
	ds_read_b128 v[162:165], v156 offset:3072
	ds_read_b128 v[166:169], v157
	ds_read_b128 v[170:173], v157 offset:1024
	ds_read_b128 v[174:177], v157 offset:2048
	ds_read_b128 v[178:181], v157 offset:3072
	s_add_u32 s20, s18, 0xffbfc080
	s_addc_u32 s21, s19, -1
	s_cmpk_eq_i32 s59, 0xfc
	s_cselect_b32 s23, s7, s21
	s_cselect_b32 s22, s6, s20
	s_cselect_b32 s21, s17, s58
	s_cselect_b32 s20, s16, s57
	ds_read_b128 v[182:185], v158
	ds_read_b128 v[186:189], v158 offset:1024
	ds_read_b128 v[190:193], v158 offset:2048
	ds_read_b128 v[194:197], v158 offset:3072
	ds_read_b128 v[198:201], v158 offset:4096
	ds_read_b128 v[202:205], v158 offset:5120
	ds_read_b128 v[206:209], v158 offset:6144
	ds_read_b128 v[210:213], v158 offset:7168
	s_add_i32 m0, s24, 0xc000
	s_nop 0
	global_load_lds_dwordx4 v136, s[18:19]
	s_add_i32 m0, s24, 0xe000
	s_nop 0
	global_load_lds_dwordx4 v140, s[18:19]
	s_sleep 2
	s_waitcnt lgkmcnt(0)
	s_waitcnt vmcnt(8)
	s_barrier
	s_setprio 2
	v_mfma_f32_16x16x32_bf16 v[124:127], v[128:131], v[182:185], v[124:127]
	v_mfma_f32_16x16x32_bf16 v[120:123], v[150:153], v[182:185], v[120:123]
	v_mfma_f32_16x16x32_bf16 v[116:119], v[128:131], v[190:193], v[116:119]
	v_mfma_f32_16x16x32_bf16 v[112:115], v[150:153], v[190:193], v[112:115]
	v_mfma_f32_16x16x32_bf16 v[108:111], v[128:131], v[198:201], v[108:111]
	v_mfma_f32_16x16x32_bf16 v[104:107], v[150:153], v[198:201], v[104:107]
	v_mfma_f32_16x16x32_bf16 v[100:103], v[128:131], v[206:209], v[100:103]
	v_mfma_f32_16x16x32_bf16 v[96:99], v[150:153], v[206:209], v[96:99]
	v_mfma_f32_16x16x32_bf16 v[124:127], v[132:135], v[186:189], v[124:127]
	v_mfma_f32_16x16x32_bf16 v[120:123], v[162:165], v[186:189], v[120:123]
	v_mfma_f32_16x16x32_bf16 v[116:119], v[132:135], v[194:197], v[116:119]
	v_mfma_f32_16x16x32_bf16 v[112:115], v[162:165], v[194:197], v[112:115]
	v_mfma_f32_16x16x32_bf16 v[108:111], v[132:135], v[202:205], v[108:111]
	v_mfma_f32_16x16x32_bf16 v[104:107], v[162:165], v[202:205], v[104:107]
	v_mfma_f32_16x16x32_bf16 v[100:103], v[132:135], v[210:213], v[100:103]
	v_mfma_f32_16x16x32_bf16 v[96:99], v[162:165], v[210:213], v[96:99]
	v_mfma_f32_16x16x32_bf16 v[68:71], v[166:169], v[182:185], v[68:71]
	v_mfma_f32_16x16x32_bf16 v[64:67], v[174:177], v[182:185], v[64:67]
	v_mfma_f32_16x16x32_bf16 v[52:55], v[166:169], v[190:193], v[52:55]
	v_mfma_f32_16x16x32_bf16 v[48:51], v[174:177], v[190:193], v[48:51]
	v_mfma_f32_16x16x32_bf16 v[44:47], v[166:169], v[198:201], v[44:47]
	v_mfma_f32_16x16x32_bf16 v[40:43], v[174:177], v[198:201], v[40:43]
	v_mfma_f32_16x16x32_bf16 v[36:39], v[166:169], v[206:209], v[36:39]
	v_mfma_f32_16x16x32_bf16 v[32:35], v[174:177], v[206:209], v[32:35]
	v_mfma_f32_16x16x32_bf16 v[68:71], v[170:173], v[186:189], v[68:71]
	v_mfma_f32_16x16x32_bf16 v[64:67], v[178:181], v[186:189], v[64:67]
	v_mfma_f32_16x16x32_bf16 v[52:55], v[170:173], v[194:197], v[52:55]
	v_mfma_f32_16x16x32_bf16 v[48:51], v[178:181], v[194:197], v[48:51]
	v_mfma_f32_16x16x32_bf16 v[44:47], v[170:173], v[202:205], v[44:47]
	v_mfma_f32_16x16x32_bf16 v[40:43], v[178:181], v[202:205], v[40:43]
	v_mfma_f32_16x16x32_bf16 v[36:39], v[170:173], v[210:213], v[36:39]
	v_mfma_f32_16x16x32_bf16 v[32:35], v[178:181], v[210:213], v[32:35]
	s_setprio 0
	ds_read_b128 v[182:185], v158 offset:16384
	ds_read_b128 v[186:189], v158 offset:17408
	ds_read_b128 v[190:193], v158 offset:18432
	ds_read_b128 v[194:197], v158 offset:19456
	ds_read_b128 v[198:201], v158 offset:20480
	ds_read_b128 v[202:205], v158 offset:21504
	ds_read_b128 v[206:209], v158 offset:22528
	ds_read_b128 v[210:213], v158 offset:23552
	s_add_u32 vcc_lo, s20, 0x404000
	s_addc_u32 vcc_hi, s21, 0
	s_add_i32 m0, s24, 0x10000
	s_nop 0
	global_load_lds_dwordx4 v138, s[20:21]
	s_add_i32 m0, s24, 0x12000
	s_nop 0
	global_load_lds_dwordx4 v142, s[20:21]
	s_add_i32 m0, s24, 0x14000
	s_nop 0
	global_load_lds_dwordx4 v138, vcc
	s_add_i32 m0, s24, 0x16000
	s_nop 0
	global_load_lds_dwordx4 v142, vcc
	s_mov_b32 m0, s24
	s_nop 0
	global_load_lds_dwordx4 v136, s[22:23]
	s_add_i32 m0, s24, 0x2000
	s_nop 0
	global_load_lds_dwordx4 v140, s[22:23]
	s_sleep 2
	s_waitcnt lgkmcnt(0)
	s_waitcnt vmcnt(8)
	s_barrier
; #define PG8_STAGE(bufoff, gbase, voff) do { _Pragma("unroll") for (int _i = 0; _i < 2; ++_i) \
;         __builtin_amdgcn_global_load_lds((const unsigned*)((const char*)(gbase) + (voff)[_i]), (PG8_LAS unsigned*)(lds + (bufoff) + ldsw + _i * 8192), 16, 0, 0); } while (0)
; #define PG8_LDA(dst, b, h) do { _Pragma("unroll") for (int m = 0; m < 4; ++m) _Pragma("unroll") for (int k = 0; k < 2; ++k) dst[m][k] = *(const PG8_LAS bf16x8*)(lds + PG8_SA(b, h) + aoff + m * 2048 + k * 1024); } while (0)
; #define PG8_LDB(dst, b, h) do { _Pragma("unroll") for (int n = 0; n < 2; ++n) _Pragma("unroll") for (int k = 0; k < 2; ++k) dst[n][k] = *(const PG8_LAS bf16x8*)(lds + PG8_SB(b, h) + boff + n * 2048 + k * 1024); } while (0)
; #define PG8_MMA(ai, bj, At, Bt) do { __builtin_amdgcn_s_setprio(1); _Pragma("unroll") for (int m = 0; m < 4; ++m) _Pragma("unroll") for (int n = 0; n < 2; ++n) _Pragma("unroll") for (int k = 0; k < 2; ++k) \
;         acc[ai][bj][m][n] = __builtin_amdgcn_mfma_f32_16x16x32_bf16(Bt[n][k], At[m][k], acc[ai][bj][m][n], 0, 0, 0); __builtin_amdgcn_s_setprio(0); } while (0)
; #define PG8_WAIT_V(n) asm volatile("s_waitcnt vmcnt(" #n ")" ::: "memory")
; #define PG8_WAIT_L(n) asm volatile("s_waitcnt lgkmcnt(" #n ")" ::: "memory")
; #define PG8_BAR __builtin_amdgcn_s_barrier()
; #define PG8_SCHED __builtin_amdgcn_sched_barrier(0)
; template <class Epi, class Sched, bool ALIGN_EPI = false, bool SP2 = false>
; __device__ __forceinline__ void gemm_phase(PG8_LAS unsigned char* lds, const Gemm g, const Sched& S, const Epi& E) {
;     ...
;             PG8_WAIT_V(8); PG8_WAIT_L(0); PG8_BAR; PG8_MMA(0, 0, At, B0); PG8_MMA(0, 1, At, B1); PG8_BAR; PG8_SCHED;
;             PG8_LDA(At, 0, 1); PG8_STAGE(PG8_SB(0, 0), b2, voffB); PG8_STAGE(PG8_SB(0, 1), b2 + hstep, voffB); PG8_STAGE(PG8_SA(0, 0), a2, voffA);
;             PG8_WAIT_V(8); PG8_WAIT_L(0); PG8_BAR; PG8_MMA(1, 0, At, B0); PG8_MMA(1, 1, At, B1); PG8_BAR; PG8_SCHED;
;             PG8_LDB(B0, 1, 0); PG8_LDB(B1, 1, 1); PG8_SCHED; PG8_LDA(At, 1, 0); PG8_STAGE(PG8_SA(0, 1), a2 + hstep, voffA);
;             PG8_WAIT_V(8); PG8_WAIT_L(0); PG8_BAR; PG8_MMA(0, 0, At, B0); PG8_MMA(0, 1, At, B1); PG8_BAR; PG8_SCHED;
	s_setprio 2
	v_mfma_f32_16x16x32_bf16 v[92:95], v[128:131], v[182:185], v[92:95]
	v_mfma_f32_16x16x32_bf16 v[88:91], v[150:153], v[182:185], v[88:91]
	v_mfma_f32_16x16x32_bf16 v[84:87], v[128:131], v[190:193], v[84:87]
	v_mfma_f32_16x16x32_bf16 v[80:83], v[150:153], v[190:193], v[80:83]
	v_mfma_f32_16x16x32_bf16 v[76:79], v[128:131], v[198:201], v[76:79]
	v_mfma_f32_16x16x32_bf16 v[72:75], v[150:153], v[198:201], v[72:75]
	v_mfma_f32_16x16x32_bf16 v[60:63], v[128:131], v[206:209], v[60:63]
	v_mfma_f32_16x16x32_bf16 v[56:59], v[150:153], v[206:209], v[56:59]
	v_mfma_f32_16x16x32_bf16 v[92:95], v[132:135], v[186:189], v[92:95]
	v_mfma_f32_16x16x32_bf16 v[88:91], v[162:165], v[186:189], v[88:91]
	v_mfma_f32_16x16x32_bf16 v[84:87], v[132:135], v[194:197], v[84:87]
	v_mfma_f32_16x16x32_bf16 v[80:83], v[162:165], v[194:197], v[80:83]
	v_mfma_f32_16x16x32_bf16 v[76:79], v[132:135], v[202:205], v[76:79]
	v_mfma_f32_16x16x32_bf16 v[72:75], v[162:165], v[202:205], v[72:75]
	v_mfma_f32_16x16x32_bf16 v[60:63], v[132:135], v[210:213], v[60:63]
	v_mfma_f32_16x16x32_bf16 v[56:59], v[162:165], v[210:213], v[56:59]
	v_mfma_f32_16x16x32_bf16 v[28:31], v[166:169], v[182:185], v[28:31]
	v_mfma_f32_16x16x32_bf16 v[24:27], v[174:177], v[182:185], v[24:27]
	v_mfma_f32_16x16x32_bf16 v[20:23], v[166:169], v[190:193], v[20:23]
	v_mfma_f32_16x16x32_bf16 v[16:19], v[174:177], v[190:193], v[16:19]
	v_mfma_f32_16x16x32_bf16 v[12:15], v[166:169], v[198:201], v[12:15]
	v_mfma_f32_16x16x32_bf16 v[8:11], v[174:177], v[198:201], v[8:11]
	v_mfma_f32_16x16x32_bf16 v[4:7], v[166:169], v[206:209], v[4:7]
	v_mfma_f32_16x16x32_bf16 v[0:3], v[174:177], v[206:209], v[0:3]
	v_mfma_f32_16x16x32_bf16 v[28:31], v[170:173], v[186:189], v[28:31]
	v_mfma_f32_16x16x32_bf16 v[24:27], v[178:181], v[186:189], v[24:27]
	v_mfma_f32_16x16x32_bf16 v[20:23], v[170:173], v[194:197], v[20:23]
	v_mfma_f32_16x16x32_bf16 v[16:19], v[178:181], v[194:197], v[16:19]
	v_mfma_f32_16x16x32_bf16 v[12:15], v[170:173], v[202:205], v[12:15]
	v_mfma_f32_16x16x32_bf16 v[8:11], v[178:181], v[202:205], v[8:11]
	v_mfma_f32_16x16x32_bf16 v[4:7], v[170:173], v[210:213], v[4:7]
	v_mfma_f32_16x16x32_bf16 v[0:3], v[178:181], v[210:213], v[0:3]
	s_setprio 0
	ds_read_b128 v[128:131], v159
	ds_read_b128 v[132:135], v159 offset:1024
	ds_read_b128 v[150:153], v159 offset:2048
	ds_read_b128 v[162:165], v159 offset:3072
	ds_read_b128 v[166:169], v160
	ds_read_b128 v[170:173], v160 offset:1024
	ds_read_b128 v[174:177], v160 offset:2048
	ds_read_b128 v[178:181], v160 offset:3072
	ds_read_b128 v[182:185], v158 offset:32768
	ds_read_b128 v[186:189], v158 offset:33792
	ds_read_b128 v[190:193], v158 offset:34816
	ds_read_b128 v[194:197], v158 offset:35840
	ds_read_b128 v[198:201], v158 offset:36864
	ds_read_b128 v[202:205], v158 offset:37888
	ds_read_b128 v[206:209], v158 offset:38912
	ds_read_b128 v[210:213], v158 offset:39936
	s_add_u32 vcc_lo, s22, 0x404000
	s_addc_u32 vcc_hi, s23, 0
	s_add_i32 m0, s24, 0x4000
	s_nop 0
	global_load_lds_dwordx4 v136, vcc
	s_add_i32 m0, s24, 0x6000
	s_nop 0
	global_load_lds_dwordx4 v140, vcc
	s_sleep 2
	s_waitcnt lgkmcnt(0)
	s_waitcnt vmcnt(8)
	s_barrier
; #define PG8_STAGE(bufoff, gbase, voff) do { _Pragma("unroll") for (int _i = 0; _i < 2; ++_i) \
;         __builtin_amdgcn_global_load_lds((const unsigned*)((const char*)(gbase) + (voff)[_i]), (PG8_LAS unsigned*)(lds + (bufoff) + ldsw + _i * 8192), 16, 0, 0); } while (0)
; #define PG8_LDA(dst, b, h) do { _Pragma("unroll") for (int m = 0; m < 4; ++m) _Pragma("unroll") for (int k = 0; k < 2; ++k) dst[m][k] = *(const PG8_LAS bf16x8*)(lds + PG8_SA(b, h) + aoff + m * 2048 + k * 1024); } while (0)
; #define PG8_LDB(dst, b, h) do { _Pragma("unroll") for (int n = 0; n < 2; ++n) _Pragma("unroll") for (int k = 0; k < 2; ++k) dst[n][k] = *(const PG8_LAS bf16x8*)(lds + PG8_SB(b, h) + boff + n * 2048 + k * 1024); } while (0)
; #define PG8_MMA(ai, bj, At, Bt) do { __builtin_amdgcn_s_setprio(1); _Pragma("unroll") for (int m = 0; m < 4; ++m) _Pragma("unroll") for (int n = 0; n < 2; ++n) _Pragma("unroll") for (int k = 0; k < 2; ++k) \
;         acc[ai][bj][m][n] = __builtin_amdgcn_mfma_f32_16x16x32_bf16(Bt[n][k], At[m][k], acc[ai][bj][m][n], 0, 0, 0); __builtin_amdgcn_s_setprio(0); } while (0)
; #define PG8_WAIT_V(n) asm volatile("s_waitcnt vmcnt(" #n ")" ::: "memory")
; #define PG8_WAIT_L(n) asm volatile("s_waitcnt lgkmcnt(" #n ")" ::: "memory")
; #define PG8_BAR __builtin_amdgcn_s_barrier()
; #define PG8_SCHED __builtin_amdgcn_sched_barrier(0)
; template <class Epi, class Sched, bool ALIGN_EPI = false, bool SP2 = false>
; __device__ __forceinline__ void gemm_phase(PG8_LAS unsigned char* lds, const Gemm g, const Sched& S, const Epi& E) {
;     ...
;             PG8_LDB(B0, 1, 0); PG8_LDB(B1, 1, 1); PG8_SCHED; PG8_LDA(At, 1, 0); PG8_STAGE(PG8_SA(0, 1), a2 + hstep, voffA);
;             PG8_WAIT_V(8); PG8_WAIT_L(0); PG8_BAR; PG8_MMA(0, 0, At, B0); PG8_MMA(0, 1, At, B1); PG8_BAR; PG8_SCHED;
;             PG8_LDA(At, 1, 1); PG8_STAGE(PG8_SB(1, 0), b3, voffB); PG8_STAGE(PG8_SB(1, 1), b3 + hstep, voffB); PG8_STAGE(PG8_SA(1, 0), a3, voffA);
;             PG8_WAIT_V(8); PG8_WAIT_L(0); PG8_BAR; PG8_MMA(1, 0, At, B0); PG8_MMA(1, 1, At, B1); PG8_BAR; PG8_SCHED;
	s_setprio 2
	v_mfma_f32_16x16x32_bf16 v[124:127], v[128:131], v[182:185], v[124:127]
	v_mfma_f32_16x16x32_bf16 v[120:123], v[150:153], v[182:185], v[120:123]
	v_mfma_f32_16x16x32_bf16 v[116:119], v[128:131], v[190:193], v[116:119]
	v_mfma_f32_16x16x32_bf16 v[112:115], v[150:153], v[190:193], v[112:115]
	v_mfma_f32_16x16x32_bf16 v[108:111], v[128:131], v[198:201], v[108:111]
	v_mfma_f32_16x16x32_bf16 v[104:107], v[150:153], v[198:201], v[104:107]
	v_mfma_f32_16x16x32_bf16 v[100:103], v[128:131], v[206:209], v[100:103]
	v_mfma_f32_16x16x32_bf16 v[96:99], v[150:153], v[206:209], v[96:99]
	v_mfma_f32_16x16x32_bf16 v[124:127], v[132:135], v[186:189], v[124:127]
	v_mfma_f32_16x16x32_bf16 v[120:123], v[162:165], v[186:189], v[120:123]
	v_mfma_f32_16x16x32_bf16 v[116:119], v[132:135], v[194:197], v[116:119]
	v_mfma_f32_16x16x32_bf16 v[112:115], v[162:165], v[194:197], v[112:115]
	v_mfma_f32_16x16x32_bf16 v[108:111], v[132:135], v[202:205], v[108:111]
	v_mfma_f32_16x16x32_bf16 v[104:107], v[162:165], v[202:205], v[104:107]
	v_mfma_f32_16x16x32_bf16 v[100:103], v[132:135], v[210:213], v[100:103]
	v_mfma_f32_16x16x32_bf16 v[96:99], v[162:165], v[210:213], v[96:99]
	v_mfma_f32_16x16x32_bf16 v[68:71], v[166:169], v[182:185], v[68:71]
	v_mfma_f32_16x16x32_bf16 v[64:67], v[174:177], v[182:185], v[64:67]
	v_mfma_f32_16x16x32_bf16 v[52:55], v[166:169], v[190:193], v[52:55]
	v_mfma_f32_16x16x32_bf16 v[48:51], v[174:177], v[190:193], v[48:51]
	v_mfma_f32_16x16x32_bf16 v[44:47], v[166:169], v[198:201], v[44:47]
	v_mfma_f32_16x16x32_bf16 v[40:43], v[174:177], v[198:201], v[40:43]
	v_mfma_f32_16x16x32_bf16 v[36:39], v[166:169], v[206:209], v[36:39]
	v_mfma_f32_16x16x32_bf16 v[32:35], v[174:177], v[206:209], v[32:35]
	v_mfma_f32_16x16x32_bf16 v[68:71], v[170:173], v[186:189], v[68:71]
	v_mfma_f32_16x16x32_bf16 v[64:67], v[178:181], v[186:189], v[64:67]
	v_mfma_f32_16x16x32_bf16 v[52:55], v[170:173], v[194:197], v[52:55]
	v_mfma_f32_16x16x32_bf16 v[48:51], v[178:181], v[194:197], v[48:51]
	v_mfma_f32_16x16x32_bf16 v[44:47], v[170:173], v[202:205], v[44:47]
	v_mfma_f32_16x16x32_bf16 v[40:43], v[178:181], v[202:205], v[40:43]
	v_mfma_f32_16x16x32_bf16 v[36:39], v[170:173], v[210:213], v[36:39]
	v_mfma_f32_16x16x32_bf16 v[32:35], v[178:181], v[210:213], v[32:35]
	s_setprio 0
	ds_read_b128 v[182:185], v158 offset:49152
	ds_read_b128 v[186:189], v158 offset:50176
	ds_read_b128 v[190:193], v158 offset:51200
	ds_read_b128 v[194:197], v158 offset:52224
	ds_read_b128 v[198:201], v158 offset:53248
	ds_read_b128 v[202:205], v158 offset:54272
	ds_read_b128 v[206:209], v158 offset:55296
	ds_read_b128 v[210:213], v158 offset:56320
	s_add_u32 s60, s20, 0x80
	s_addc_u32 s61, s21, 0
	s_add_u32 vcc_lo, s60, 0x404000
	s_addc_u32 vcc_hi, s61, 0
	s_add_i32 m0, s24, 0x18000
	s_nop 0
	global_load_lds_dwordx4 v138, s[60:61]
	s_add_i32 m0, s24, 0x1a000
	s_nop 0
	global_load_lds_dwordx4 v142, s[60:61]
	s_add_i32 m0, s24, 0x1c000
	s_nop 0
	global_load_lds_dwordx4 v138, vcc
	s_add_i32 m0, s24, 0x1e000
	s_nop 0
	global_load_lds_dwordx4 v142, vcc
	s_add_u32 s60, s22, 0x80
	s_addc_u32 s61, s23, 0
	s_add_i32 m0, s24, 0x8000
	s_nop 0
	global_load_lds_dwordx4 v136, s[60:61]
	s_add_i32 m0, s24, 0xa000
	s_nop 0
	global_load_lds_dwordx4 v140, s[60:61]
	s_sleep 2
	s_waitcnt lgkmcnt(0)
	s_waitcnt vmcnt(8)
	s_barrier
	s_setprio 2
	v_mfma_f32_16x16x32_bf16 v[92:95], v[128:131], v[182:185], v[92:95]
	v_mfma_f32_16x16x32_bf16 v[88:91], v[150:153], v[182:185], v[88:91]
	v_mfma_f32_16x16x32_bf16 v[84:87], v[128:131], v[190:193], v[84:87]
	v_mfma_f32_16x16x32_bf16 v[80:83], v[150:153], v[190:193], v[80:83]
	v_mfma_f32_16x16x32_bf16 v[76:79], v[128:131], v[198:201], v[76:79]
	v_mfma_f32_16x16x32_bf16 v[72:75], v[150:153], v[198:201], v[72:75]
	v_mfma_f32_16x16x32_bf16 v[60:63], v[128:131], v[206:209], v[60:63]
	v_mfma_f32_16x16x32_bf16 v[56:59], v[150:153], v[206:209], v[56:59]
	v_mfma_f32_16x16x32_bf16 v[92:95], v[132:135], v[186:189], v[92:95]
	v_mfma_f32_16x16x32_bf16 v[88:91], v[162:165], v[186:189], v[88:91]
	v_mfma_f32_16x16x32_bf16 v[84:87], v[132:135], v[194:197], v[84:87]
	v_mfma_f32_16x16x32_bf16 v[80:83], v[162:165], v[194:197], v[80:83]
	v_mfma_f32_16x16x32_bf16 v[76:79], v[132:135], v[202:205], v[76:79]
	v_mfma_f32_16x16x32_bf16 v[72:75], v[162:165], v[202:205], v[72:75]
	v_mfma_f32_16x16x32_bf16 v[60:63], v[132:135], v[210:213], v[60:63]
	v_mfma_f32_16x16x32_bf16 v[56:59], v[162:165], v[210:213], v[56:59]
	v_mfma_f32_16x16x32_bf16 v[28:31], v[166:169], v[182:185], v[28:31]
	v_mfma_f32_16x16x32_bf16 v[24:27], v[174:177], v[182:185], v[24:27]
	v_mfma_f32_16x16x32_bf16 v[20:23], v[166:169], v[190:193], v[20:23]
	v_mfma_f32_16x16x32_bf16 v[16:19], v[174:177], v[190:193], v[16:19]
	v_mfma_f32_16x16x32_bf16 v[12:15], v[166:169], v[198:201], v[12:15]
	v_mfma_f32_16x16x32_bf16 v[8:11], v[174:177], v[198:201], v[8:11]
	v_mfma_f32_16x16x32_bf16 v[4:7], v[166:169], v[206:209], v[4:7]
	v_mfma_f32_16x16x32_bf16 v[0:3], v[174:177], v[206:209], v[0:3]
	v_mfma_f32_16x16x32_bf16 v[28:31], v[170:173], v[186:189], v[28:31]
	v_mfma_f32_16x16x32_bf16 v[24:27], v[178:181], v[186:189], v[24:27]
	v_mfma_f32_16x16x32_bf16 v[20:23], v[170:173], v[194:197], v[20:23]
	v_mfma_f32_16x16x32_bf16 v[16:19], v[178:181], v[194:197], v[16:19]
	v_mfma_f32_16x16x32_bf16 v[12:15], v[170:173], v[202:205], v[12:15]
	v_mfma_f32_16x16x32_bf16 v[8:11], v[178:181], v[202:205], v[8:11]
	v_mfma_f32_16x16x32_bf16 v[4:7], v[170:173], v[210:213], v[4:7]
	v_mfma_f32_16x16x32_bf16 v[0:3], v[178:181], v[210:213], v[0:3]
	s_setprio 0
	s_add_i32 s59, s59, 2
	s_add_u32 s18, s18, 0x100
	s_addc_u32 s19, s19, 0
	s_add_u32 s57, s57, 0x100
	s_addc_u32 s58, s58, 0
	s_cmpk_gt_u32 s59, 0xfd
	s_cbranch_scc0 .Lf2_h1
